# P6 row loop hand-written: row loads and the 16 ada loads of a row all in flight, sample-row partial sums 16 loads deep
# speedup vs baseline: 1.0275x; 1.0099x over previous
.LBB0_738:
	s_or_b64 exec, exec, s[4:5]
	v_mov_b32_e32 v95, 0
	v_lshlrev_b32_e32 v94, 4, v170
	v_lshl_add_u64 v[34:35], s[50:51], 0, v[94:95]
	s_movk_i32 s0, 0x1000
	v_add_co_u32_e32 v54, vcc, s0, v34
	v_lshl_add_u64 v[36:37], s[16:17], 0, v[94:95]
	s_nop 0
	v_addc_co_u32_e32 v55, vcc, 0, v35, vcc
	v_add_co_u32_e32 v62, vcc, s0, v36
	s_cmpk_lg_i32 s96, 0x100
	s_nop 0
	v_addc_co_u32_e32 v63, vcc, 0, v37, vcc
	s_cselect_b64 s[12:13], -1, 0
	s_add_i32 s1, s34, 0x207f
	s_and_b32 s3, s68, 15
	s_waitcnt lgkmcnt(0)
	s_barrier
	global_load_dwordx4 v[2:5], v94, s[50:51]
	global_load_dwordx4 v[6:9], v94, s[50:51] offset:1024
	global_load_dwordx4 v[10:13], v94, s[16:17]
	global_load_dwordx4 v[14:17], v94, s[16:17] offset:1024
	global_load_dwordx4 v[18:21], v94, s[50:51] offset:2048
	global_load_dwordx4 v[22:25], v94, s[50:51] offset:3072
	global_load_dwordx4 v[26:29], v94, s[16:17] offset:2048
	global_load_dwordx4 v[30:33], v94, s[16:17] offset:3072
	global_load_dwordx4 v[34:37], v[54:55], off
	global_load_dwordx4 v[38:41], v[54:55], off offset:1024
	global_load_dwordx4 v[42:45], v[62:63], off
	global_load_dwordx4 v[46:49], v[62:63], off offset:1024
	global_load_dwordx4 v[50:53], v[54:55], off offset:2048
	s_nop 0
	global_load_dwordx4 v[54:57], v[54:55], off offset:3072
	s_nop 0
	global_load_dwordx4 v[58:61], v[62:63], off offset:2048
	s_nop 0
	global_load_dwordx4 v[62:65], v[62:63], off offset:3072
	s_cmp_eq_u32 s3, 0
	s_cselect_b64 s[4:5], -1, 0
	s_ashr_i32 s8, s68, 4
	s_cmpk_lt_i32 s8, 0x80
	s_cselect_b64 s[6:7], -1, 0
	s_and_b64 s[4:5], s[4:5], s[6:7]
	s_cmp_eq_u32 s3, 8
	s_cselect_b64 s[6:7], -1, 0
	s_cmpk_lt_i32 s68, 0x808
	s_mul_i32 s3, s96, 24
	s_cselect_b64 s[10:11], -1, 0
	s_add_i32 s3, s3, s68
	s_and_b64 s[6:7], s[10:11], s[6:7]
	s_add_i32 s10, s3, -8
	s_and_b64 s[6:7], s[6:7], exec
	s_cselect_b32 s69, s10, -1
	s_addk_i32 s8, 0x2000
	s_and_b64 s[4:5], s[4:5], exec
	s_cselect_b32 s72, s8, s3
	v_or_b32_e32 v66, 0x1000, v171
	s_mov_b32 s3, 0x5555556
	v_mul_hi_u32 v67, v66, s3
	v_lshl_add_u32 v98, v67, 4, v66
	v_or_b32_e32 v66, 0x1100, v171
	v_mul_hi_u32 v67, v66, s3
	v_lshl_add_u32 v100, v67, 4, v66
	v_or_b32_e32 v66, 0x1200, v171
	v_mul_hi_u32 v67, v66, s3
	v_lshl_add_u32 v102, v67, 4, v66
	v_or_b32_e32 v66, 0x1300, v171
	v_mul_hi_u32 v67, v66, s3
	v_lshl_add_u32 v104, v67, 4, v66
	v_or_b32_e32 v66, 0x1400, v171
	v_mul_hi_u32 v67, v66, s3
	v_lshl_add_u32 v106, v67, 4, v66
	v_or_b32_e32 v66, 0x1500, v171
	v_mul_hi_u32 v67, v66, s3
	v_lshl_add_u32 v108, v67, 4, v66
	v_or_b32_e32 v66, 0x1600, v171
	v_mul_hi_u32 v67, v66, s3
	v_lshl_add_u32 v110, v67, 4, v66
	v_or_b32_e32 v66, 0x1700, v171
	v_mul_hi_u32 v67, v66, s3
	v_lshl_add_u32 v112, v67, 4, v66
	v_or_b32_e32 v66, 0x2000, v171
	v_mul_hi_u32 v67, v66, s3
	v_lshl_add_u32 v116, v67, 4, v66
	v_or_b32_e32 v66, 0x1800, v171
	v_mul_hi_u32 v67, v66, s3
	v_lshl_add_u32 v118, v67, 4, v66
	v_or_b32_e32 v66, 0x2100, v171
	v_mul_hi_u32 v67, v66, s3
	v_lshl_add_u32 v120, v67, 4, v66
	v_or_b32_e32 v66, 0x1900, v171
	v_mul_hi_u32 v67, v66, s3
	v_lshl_add_u32 v122, v67, 4, v66
	v_or_b32_e32 v66, 0x2200, v171
	v_mul_hi_u32 v67, v66, s3
	v_lshl_add_u32 v124, v67, 4, v66
	v_or_b32_e32 v66, 0x1a00, v171
	v_mul_hi_u32 v67, v66, s3
	v_lshl_add_u32 v126, v67, 4, v66
	v_or_b32_e32 v66, 0x2300, v171
	v_mul_hi_u32 v67, v66, s3
	v_lshl_add_u32 v128, v67, 4, v66
	v_or_b32_e32 v66, 0x1b00, v171
	v_mul_hi_u32 v67, v66, s3
	v_lshl_add_u32 v130, v67, 4, v66
	v_or_b32_e32 v66, 0x2400, v171
	v_mul_hi_u32 v67, v66, s3
	v_lshl_add_u32 v132, v67, 4, v66
	v_or_b32_e32 v66, 0x1c00, v171
	v_mul_hi_u32 v67, v66, s3
	v_lshl_add_u32 v134, v67, 4, v66
	v_or_b32_e32 v66, 0x2500, v171
	v_mul_hi_u32 v67, v66, s3
	v_lshl_add_u32 v136, v67, 4, v66
	v_or_b32_e32 v66, 0x1d00, v171
	v_mul_hi_u32 v67, v66, s3
	v_lshl_add_u32 v138, v67, 4, v66
	v_or_b32_e32 v66, 0x2600, v171
	v_lshl_add_u64 v[174:175], s[42:43], 0, v[94:95]
	s_mov_b64 s[4:5], 0x1000
	v_mul_hi_u32 v67, v66, s3
	v_lshl_add_u64 v[176:177], v[174:175], 0, s[4:5]
	s_mov_b64 s[4:5], 0x1400
	v_lshl_add_u32 v140, v67, 4, v66
	v_or_b32_e32 v66, 0x1e00, v171
	v_lshl_add_u64 v[178:179], v[174:175], 0, s[4:5]
	s_mov_b64 s[4:5], 0x1800
	v_mul_hi_u32 v67, v66, s3
	v_lshl_add_u64 v[180:181], v[174:175], 0, s[4:5]
	s_mov_b64 s[4:5], 0x1c00
	v_lshl_add_u32 v142, v67, 4, v66
	v_or_b32_e32 v66, 0x2700, v171
	v_lshl_add_u64 v[182:183], v[174:175], 0, s[4:5]
	v_mul_hi_u32 v67, v66, s3
	s_abs_i32 s4, s34
	v_lshl_add_u32 v144, v67, 4, v66
	v_cvt_f32_u32_e32 v66, s4
	s_sub_i32 s5, 0, s4
	v_or_b32_e32 v67, 0x1f00, v171
	v_mul_hi_u32 v68, v67, s3
	v_rcp_iflag_f32_e32 v66, v66
	s_xor_b32 s3, s1, s34
	s_abs_i32 s1, s1
	s_ashr_i32 s3, s3, 31
	v_mul_f32_e32 v66, 0x4f7ffffe, v66
	v_cvt_u32_f32_e32 v66, v66
	v_mov_b32_e32 v159, v95
	s_mov_b32 s9, 0
	v_lshl_add_u64 v[96:97], s[44:45], 0, v[158:159]
	v_readfirstlane_b32 s6, v66
	s_mul_i32 s5, s5, s6
	s_mul_hi_u32 s5, s6, s5
	s_add_i32 s6, s6, s5
	s_mul_hi_u32 s5, s1, s6
	s_mul_i32 s6, s5, s4
	s_sub_i32 s1, s1, s6
	s_add_i32 s6, s5, 1
	s_sub_i32 s7, s1, s4
	s_cmp_ge_u32 s1, s4
	s_cselect_b32 s5, s6, s5
	s_cselect_b32 s1, s7, s1
	s_add_i32 s6, s5, 1
	s_cmp_ge_u32 s1, s4
	s_cselect_b32 s1, s6, s5
	s_xor_b32 s1, s1, s3
	v_mbcnt_lo_u32_b32 v66, -1, 0
	v_lshl_add_u64 v[172:173], s[40:41], 0, v[94:95]
	v_mov_b32_e32 v99, v95
	v_mov_b32_e32 v101, v95
	v_mov_b32_e32 v103, v95
	v_mov_b32_e32 v105, v95
	v_mov_b32_e32 v107, v95
	v_mov_b32_e32 v109, v95
	v_mov_b32_e32 v111, v95
	v_mov_b32_e32 v113, v95
	v_lshl_add_u64 v[114:115], s[54:55], 0, v[94:95]
	v_mov_b32_e32 v117, v95
	v_mov_b32_e32 v119, v95
	v_mov_b32_e32 v121, v95
	v_mov_b32_e32 v123, v95
	v_mov_b32_e32 v125, v95
	v_mov_b32_e32 v127, v95
	v_mov_b32_e32 v129, v95
	v_mov_b32_e32 v131, v95
	v_mov_b32_e32 v133, v95
	v_mov_b32_e32 v135, v95
	v_mov_b32_e32 v137, v95
	v_mov_b32_e32 v139, v95
	v_mov_b32_e32 v141, v95
	v_mov_b32_e32 v143, v95
	v_mov_b32_e32 v145, v95
	v_lshl_add_u32 v146, v68, 4, v67
	v_mov_b32_e32 v147, v95
	s_sub_i32 s73, s1, s3
	s_mov_b32 s1, 0x100000
	s_mov_b32 s3, 0x200000
	s_mov_b32 s10, 0x300000
	s_mov_b32 s11, 0x400000
	s_mov_b32 s17, 0x500000
	s_mov_b32 s50, 0x600000
	s_mov_b32 s51, 0x700000
	s_mov_b32 s16, 0x3f9837f0
	v_mov_b32_e32 v151, 0x3727c5ac
	s_mov_b32 s54, 0xf800000
	v_mov_b32_e32 v153, 0x260
	s_movk_i32 s55, 0x7fff
	s_mov_b32 s56, 0xffff0000
	v_mov_b32_e32 v155, 0x2000
	v_mov_b32_e32 v157, 0x207f
	v_mbcnt_hi_u32_b32 v211, -1, v66
	s_mov_b32 s57, s68
	s_mov_b32 s58, s68
	s_mov_b32 s59, 0
	v_cndmask_b32_e64 v66, 0, 1, s[12:13]
	v_cmp_ne_u32_e64 s[4:5], 1, v66
	s_mov_b32 s3, 0x3f9837f0
	v_lshlrev_b32_e32 v129, 4, v170
	v_add_u32_e32 v131, 0x1000, v129
	v_lshlrev_b32_e32 v117, 3, v170
	v_xor_b32_e32 v99, 1, v211
	v_lshlrev_b32_e32 v99, 2, v99
	v_xor_b32_e32 v101, 2, v211
	v_lshlrev_b32_e32 v101, 2, v101
	v_xor_b32_e32 v103, 4, v211
	v_lshlrev_b32_e32 v103, 2, v103
	v_xor_b32_e32 v105, 8, v211
	v_lshlrev_b32_e32 v105, 2, v105
	v_xor_b32_e32 v107, 16, v211
	v_lshlrev_b32_e32 v107, 2, v107
	v_xor_b32_e32 v119, 32, v211
	v_lshlrev_b32_e32 v119, 2, v119
	s_mov_b32 s0, s68
	s_lshl_b32 s1, s0, 13
	s_add_u32 s6, s40, s1
	s_addc_u32 s7, s41, 0
	s_lshl_b32 s1, s0, 12
	s_add_u32 s10, s44, s1
	s_addc_u32 s11, s45, 0
	s_lshr_b32 s1, s0, 11
	s_lshl_b32 s1, s1, 16
	s_add_u32 s16, s14, s1
	s_addc_u32 s17, s15, 0
	global_load_dwordx4 v[66:69], v129, s[6:7]
	global_load_dwordx4 v[70:73], v129, s[6:7] offset:1024
	global_load_dwordx4 v[74:77], v129, s[6:7] offset:2048
	global_load_dwordx4 v[78:81], v129, s[6:7] offset:3072
	global_load_dwordx4 v[82:85], v131, s[6:7]
	global_load_dwordx4 v[86:89], v131, s[6:7] offset:1024
	global_load_dwordx4 v[90:93], v131, s[6:7] offset:2048
	global_load_dwordx4 v[94:97], v131, s[6:7] offset:3072
	v_lshlrev_b32_e32 v151, 2, v116
	global_load_dwordx4 v[158:161], v151, s[16:17]
	v_lshlrev_b32_e32 v151, 2, v118
	global_load_dwordx4 v[220:223], v151, s[16:17]
	v_lshlrev_b32_e32 v151, 2, v120
	global_load_dwordx4 v[162:165], v151, s[16:17]
	v_lshlrev_b32_e32 v151, 2, v122
	global_load_dwordx4 v[224:227], v151, s[16:17]
	v_lshlrev_b32_e32 v151, 2, v124
	global_load_dwordx4 v[166:169], v151, s[16:17]
	v_lshlrev_b32_e32 v151, 2, v126
	global_load_dwordx4 v[228:231], v151, s[16:17]
	v_lshlrev_b32_e32 v151, 2, v128
	global_load_dwordx4 v[176:179], v151, s[16:17]
	v_lshlrev_b32_e32 v151, 2, v130
	global_load_dwordx4 v[232:235], v151, s[16:17]
	v_lshlrev_b32_e32 v151, 2, v132
	global_load_dwordx4 v[180:183], v151, s[16:17]
	v_lshlrev_b32_e32 v151, 2, v134
	global_load_dwordx4 v[236:239], v151, s[16:17]
	v_lshlrev_b32_e32 v151, 2, v136
	global_load_dwordx4 v[184:187], v151, s[16:17]
	v_lshlrev_b32_e32 v151, 2, v138
	global_load_dwordx4 v[240:243], v151, s[16:17]
	v_lshlrev_b32_e32 v151, 2, v140
	global_load_dwordx4 v[212:215], v151, s[16:17]
	v_lshlrev_b32_e32 v151, 2, v142
	global_load_dwordx4 v[244:247], v151, s[16:17]
	v_lshlrev_b32_e32 v151, 2, v144
	global_load_dwordx4 v[216:219], v151, s[16:17]
	v_lshlrev_b32_e32 v151, 2, v146
	global_load_dwordx4 v[248:251], v151, s[16:17]
	s_waitcnt vmcnt(23)
	v_add_f32_e32 v151, v66, v67
	v_add_f32_e32 v155, v68, v69
	v_add_f32_e32 v151, v151, v155
	v_add_f32_e32 v153, 0, v151
	s_waitcnt vmcnt(22)
	v_add_f32_e32 v151, v70, v71
	v_add_f32_e32 v155, v72, v73
	v_add_f32_e32 v151, v151, v155
	v_add_f32_e32 v153, v153, v151
	s_waitcnt vmcnt(21)
	v_add_f32_e32 v151, v74, v75
	v_add_f32_e32 v155, v76, v77
	v_add_f32_e32 v151, v151, v155
	v_add_f32_e32 v153, v153, v151
	s_waitcnt vmcnt(20)
	v_add_f32_e32 v151, v78, v79
	v_add_f32_e32 v155, v80, v81
	v_add_f32_e32 v151, v151, v155
	v_add_f32_e32 v153, v153, v151
	s_waitcnt vmcnt(19)
	v_add_f32_e32 v151, v82, v83
	v_add_f32_e32 v155, v84, v85
	v_add_f32_e32 v151, v151, v155
	v_add_f32_e32 v153, v153, v151
	s_waitcnt vmcnt(18)
	v_add_f32_e32 v151, v86, v87
	v_add_f32_e32 v155, v88, v89
	v_add_f32_e32 v151, v151, v155
	v_add_f32_e32 v153, v153, v151
	s_waitcnt vmcnt(17)
	v_add_f32_e32 v151, v90, v91
	v_add_f32_e32 v155, v92, v93
	v_add_f32_e32 v151, v151, v155
	v_add_f32_e32 v153, v153, v151
	s_waitcnt vmcnt(16)
	v_add_f32_e32 v151, v94, v95
	v_add_f32_e32 v155, v96, v97
	v_add_f32_e32 v151, v151, v155
	v_add_f32_e32 v153, v153, v151
	ds_bpermute_b32 v151, v99, v153
	s_waitcnt lgkmcnt(0)
	v_add_f32_e32 v153, v153, v151
	ds_bpermute_b32 v151, v101, v153
	s_waitcnt lgkmcnt(0)
	v_add_f32_e32 v153, v153, v151
	ds_bpermute_b32 v151, v103, v153
	s_waitcnt lgkmcnt(0)
	v_add_f32_e32 v153, v153, v151
	ds_bpermute_b32 v151, v105, v153
	s_waitcnt lgkmcnt(0)
	v_add_f32_e32 v153, v153, v151
	ds_bpermute_b32 v151, v107, v153
	s_waitcnt lgkmcnt(0)
	v_add_f32_e32 v153, v153, v151
	ds_bpermute_b32 v151, v119, v153
	s_waitcnt lgkmcnt(0)
	v_add_f32_e32 v153, v153, v151
	v_fmac_f32_e32 v66, 0xba000000, v153
	v_fmac_f32_e32 v67, 0xba000000, v153
	v_fmac_f32_e32 v68, 0xba000000, v153
	v_fmac_f32_e32 v69, 0xba000000, v153
	v_fmac_f32_e32 v70, 0xba000000, v153
	v_fmac_f32_e32 v71, 0xba000000, v153
	v_fmac_f32_e32 v72, 0xba000000, v153
	v_fmac_f32_e32 v73, 0xba000000, v153
	v_fmac_f32_e32 v74, 0xba000000, v153
	v_fmac_f32_e32 v75, 0xba000000, v153
	v_fmac_f32_e32 v76, 0xba000000, v153
	v_fmac_f32_e32 v77, 0xba000000, v153
	v_fmac_f32_e32 v78, 0xba000000, v153
	v_fmac_f32_e32 v79, 0xba000000, v153
	v_fmac_f32_e32 v80, 0xba000000, v153
	v_fmac_f32_e32 v81, 0xba000000, v153
	v_fmac_f32_e32 v82, 0xba000000, v153
	v_fmac_f32_e32 v83, 0xba000000, v153
	v_fmac_f32_e32 v84, 0xba000000, v153
	v_fmac_f32_e32 v85, 0xba000000, v153
	v_fmac_f32_e32 v86, 0xba000000, v153
	v_fmac_f32_e32 v87, 0xba000000, v153
	v_fmac_f32_e32 v88, 0xba000000, v153
	v_fmac_f32_e32 v89, 0xba000000, v153
	v_fmac_f32_e32 v90, 0xba000000, v153
	v_fmac_f32_e32 v91, 0xba000000, v153
	v_fmac_f32_e32 v92, 0xba000000, v153
	v_fmac_f32_e32 v93, 0xba000000, v153
	v_fmac_f32_e32 v94, 0xba000000, v153
	v_fmac_f32_e32 v95, 0xba000000, v153
	v_fmac_f32_e32 v96, 0xba000000, v153
	v_fmac_f32_e32 v97, 0xba000000, v153
	v_mul_f32_e32 v151, v67, v67
	v_fma_f32 v151, v66, v66, v151
	v_mul_f32_e32 v155, v69, v69
	v_fma_f32 v155, v68, v68, v155
	v_add_f32_e32 v151, v151, v155
	v_add_f32_e32 v157, 0, v151
	v_mul_f32_e32 v151, v71, v71
	v_fma_f32 v151, v70, v70, v151
	v_mul_f32_e32 v155, v73, v73
	v_fma_f32 v155, v72, v72, v155
	v_add_f32_e32 v151, v151, v155
	v_add_f32_e32 v157, v157, v151
	v_mul_f32_e32 v151, v75, v75
	v_fma_f32 v151, v74, v74, v151
	v_mul_f32_e32 v155, v77, v77
	v_fma_f32 v155, v76, v76, v155
	v_add_f32_e32 v151, v151, v155
	v_add_f32_e32 v157, v157, v151
	v_mul_f32_e32 v151, v79, v79
	v_fma_f32 v151, v78, v78, v151
	v_mul_f32_e32 v155, v81, v81
	v_fma_f32 v155, v80, v80, v155
	v_add_f32_e32 v151, v151, v155
	v_add_f32_e32 v157, v157, v151
	v_mul_f32_e32 v151, v83, v83
	v_fma_f32 v151, v82, v82, v151
	v_mul_f32_e32 v155, v85, v85
	v_fma_f32 v155, v84, v84, v155
	v_add_f32_e32 v151, v151, v155
	v_add_f32_e32 v157, v157, v151
	v_mul_f32_e32 v151, v87, v87
	v_fma_f32 v151, v86, v86, v151
	v_mul_f32_e32 v155, v89, v89
	v_fma_f32 v155, v88, v88, v155
	v_add_f32_e32 v151, v151, v155
	v_add_f32_e32 v157, v157, v151
	v_mul_f32_e32 v151, v91, v91
	v_fma_f32 v151, v90, v90, v151
	v_mul_f32_e32 v155, v93, v93
	v_fma_f32 v155, v92, v92, v155
	v_add_f32_e32 v151, v151, v155
	v_add_f32_e32 v157, v157, v151
	v_mul_f32_e32 v151, v95, v95
	v_fma_f32 v151, v94, v94, v151
	v_mul_f32_e32 v155, v97, v97
	v_fma_f32 v155, v96, v96, v155
	v_add_f32_e32 v151, v151, v155
	v_add_f32_e32 v157, v157, v151
	ds_bpermute_b32 v151, v99, v157
	s_waitcnt lgkmcnt(0)
	v_add_f32_e32 v157, v157, v151
	ds_bpermute_b32 v151, v101, v157
	s_waitcnt lgkmcnt(0)
	v_add_f32_e32 v157, v157, v151
	ds_bpermute_b32 v151, v103, v157
	s_waitcnt lgkmcnt(0)
	v_add_f32_e32 v157, v157, v151
	ds_bpermute_b32 v151, v105, v157
	s_waitcnt lgkmcnt(0)
	v_add_f32_e32 v157, v157, v151
	ds_bpermute_b32 v151, v107, v157
	s_waitcnt lgkmcnt(0)
	v_add_f32_e32 v157, v157, v151
	ds_bpermute_b32 v151, v119, v157
	s_waitcnt lgkmcnt(0)
	v_add_f32_e32 v157, v157, v151
	v_mov_b32_e32 v254, 0x3727c5ac
	v_fmamk_f32 v157, v157, 0x3a000000, v254
	v_mul_f32_e32 v151, 0x4f800000, v157
	s_mov_b32 s9, 0xf800000
	v_cmp_gt_f32_e32 vcc, s9, v157
	s_nop 1
	v_cndmask_b32_e32 v157, v157, v151, vcc
	v_sqrt_f32_e32 v151, v157
	s_nop 0
	v_add_u32_e32 v203, -1, v151
	v_fma_f32 v204, -v203, v151, v157
	v_cmp_ge_f32_e64 s[88:89], 0, v204
	v_add_u32_e32 v204, 1, v151
	s_nop 0
	v_cndmask_b32_e64 v203, v151, v203, s[88:89]
	v_fma_f32 v151, -v204, v151, v157
	v_cmp_lt_f32_e64 s[88:89], 0, v151
	s_nop 1
	v_cndmask_b32_e64 v151, v203, v204, s[88:89]
	v_mul_f32_e32 v203, 0x37800000, v151
	v_cndmask_b32_e32 v151, v151, v203, vcc
	v_mov_b32_e32 v203, 0x260
	v_cmp_class_f32_e32 vcc, v157, v203
	s_nop 1
	v_cndmask_b32_e32 v157, v151, v157, vcc
	v_div_scale_f32 v151, s[88:89], v157, v157, 1.0
	v_rcp_f32_e32 v203, v151
	s_nop 0
	v_fma_f32 v204, -v151, v203, 1.0
	v_fmac_f32_e32 v203, v204, v203
	v_div_scale_f32 v204, vcc, 1.0, v157, 1.0
	v_mul_f32_e32 v205, v204, v203
	v_fma_f32 v254, -v151, v205, v204
	v_fmac_f32_e32 v205, v254, v203
	v_fma_f32 v151, -v151, v205, v204
	v_div_fmas_f32 v151, v151, v203, v205
	v_div_fixup_f32 v155, v151, v157, 1.0
	v_mul_f32_e32 v66, v66, v155
	v_mul_f32_e32 v67, v67, v155
	v_mul_f32_e32 v68, v68, v155
	v_mul_f32_e32 v69, v69, v155
	v_pk_fma_f32 v[66:67], v[2:3], v[66:67], v[10:11]
	v_pk_fma_f32 v[68:69], v[4:5], v[68:69], v[12:13]
	global_store_dwordx4 v129, v[66:69], s[6:7]
	s_waitcnt vmcnt(15)
	v_pk_add_f32 v[158:159], v[158:159], 1.0 op_sel_hi:[1,0]
	v_pk_add_f32 v[160:161], v[160:161], 1.0 op_sel_hi:[1,0]
	v_pk_fma_f32 v[158:159], v[158:159], v[66:67], v[220:221]
	v_pk_fma_f32 v[160:161], v[160:161], v[68:69], v[222:223]
	v_cvt_pk_bf16_f32 v158, v158, v159
	v_cvt_pk_bf16_f32 v159, v160, v161
	global_store_dwordx2 v117, v[158:159], s[10:11]
	v_mul_f32_e32 v70, v70, v155
	v_mul_f32_e32 v71, v71, v155
	v_mul_f32_e32 v72, v72, v155
	v_mul_f32_e32 v73, v73, v155
	v_pk_fma_f32 v[70:71], v[6:7], v[70:71], v[14:15]
	v_pk_fma_f32 v[72:73], v[8:9], v[72:73], v[16:17]
	global_store_dwordx4 v129, v[70:73], s[6:7] offset:1024
	s_waitcnt vmcnt(15)
	v_pk_add_f32 v[162:163], v[162:163], 1.0 op_sel_hi:[1,0]
	v_pk_add_f32 v[164:165], v[164:165], 1.0 op_sel_hi:[1,0]
	v_pk_fma_f32 v[162:163], v[162:163], v[70:71], v[224:225]
	v_pk_fma_f32 v[164:165], v[164:165], v[72:73], v[226:227]
	v_cvt_pk_bf16_f32 v162, v162, v163
	v_cvt_pk_bf16_f32 v163, v164, v165
	global_store_dwordx2 v117, v[162:163], s[10:11] offset:512
	v_mul_f32_e32 v74, v74, v155
	v_mul_f32_e32 v75, v75, v155
	v_mul_f32_e32 v76, v76, v155
	v_mul_f32_e32 v77, v77, v155
	v_pk_fma_f32 v[74:75], v[18:19], v[74:75], v[26:27]
	v_pk_fma_f32 v[76:77], v[20:21], v[76:77], v[28:29]
	global_store_dwordx4 v129, v[74:77], s[6:7] offset:2048
	s_waitcnt vmcnt(15)
	v_pk_add_f32 v[166:167], v[166:167], 1.0 op_sel_hi:[1,0]
	v_pk_add_f32 v[168:169], v[168:169], 1.0 op_sel_hi:[1,0]
	v_pk_fma_f32 v[166:167], v[166:167], v[74:75], v[228:229]
	v_pk_fma_f32 v[168:169], v[168:169], v[76:77], v[230:231]
	v_cvt_pk_bf16_f32 v166, v166, v167
	v_cvt_pk_bf16_f32 v167, v168, v169
	global_store_dwordx2 v117, v[166:167], s[10:11] offset:1024
	v_mul_f32_e32 v78, v78, v155
	v_mul_f32_e32 v79, v79, v155
	v_mul_f32_e32 v80, v80, v155
	v_mul_f32_e32 v81, v81, v155
	v_pk_fma_f32 v[78:79], v[22:23], v[78:79], v[30:31]
	v_pk_fma_f32 v[80:81], v[24:25], v[80:81], v[32:33]
	global_store_dwordx4 v129, v[78:81], s[6:7] offset:3072
	s_waitcnt vmcnt(15)
	v_pk_add_f32 v[176:177], v[176:177], 1.0 op_sel_hi:[1,0]
	v_pk_add_f32 v[178:179], v[178:179], 1.0 op_sel_hi:[1,0]
	v_pk_fma_f32 v[176:177], v[176:177], v[78:79], v[232:233]
	v_pk_fma_f32 v[178:179], v[178:179], v[80:81], v[234:235]
	v_cvt_pk_bf16_f32 v176, v176, v177
	v_cvt_pk_bf16_f32 v177, v178, v179
	global_store_dwordx2 v117, v[176:177], s[10:11] offset:1536
	v_mul_f32_e32 v82, v82, v155
	v_mul_f32_e32 v83, v83, v155
	v_mul_f32_e32 v84, v84, v155
	v_mul_f32_e32 v85, v85, v155
	v_pk_fma_f32 v[82:83], v[34:35], v[82:83], v[42:43]
	v_pk_fma_f32 v[84:85], v[36:37], v[84:85], v[44:45]
	global_store_dwordx4 v131, v[82:85], s[6:7]
	s_waitcnt vmcnt(15)
	v_pk_add_f32 v[180:181], v[180:181], 1.0 op_sel_hi:[1,0]
	v_pk_add_f32 v[182:183], v[182:183], 1.0 op_sel_hi:[1,0]
	v_pk_fma_f32 v[180:181], v[180:181], v[82:83], v[236:237]
	v_pk_fma_f32 v[182:183], v[182:183], v[84:85], v[238:239]
	v_cvt_pk_bf16_f32 v180, v180, v181
	v_cvt_pk_bf16_f32 v181, v182, v183
	global_store_dwordx2 v117, v[180:181], s[10:11] offset:2048
	v_mul_f32_e32 v86, v86, v155
	v_mul_f32_e32 v87, v87, v155
	v_mul_f32_e32 v88, v88, v155
	v_mul_f32_e32 v89, v89, v155
	v_pk_fma_f32 v[86:87], v[38:39], v[86:87], v[46:47]
	v_pk_fma_f32 v[88:89], v[40:41], v[88:89], v[48:49]
	global_store_dwordx4 v131, v[86:89], s[6:7] offset:1024
	s_waitcnt vmcnt(15)
	v_pk_add_f32 v[184:185], v[184:185], 1.0 op_sel_hi:[1,0]
	v_pk_add_f32 v[186:187], v[186:187], 1.0 op_sel_hi:[1,0]
	v_pk_fma_f32 v[184:185], v[184:185], v[86:87], v[240:241]
	v_pk_fma_f32 v[186:187], v[186:187], v[88:89], v[242:243]
	v_cvt_pk_bf16_f32 v184, v184, v185
	v_cvt_pk_bf16_f32 v185, v186, v187
	global_store_dwordx2 v117, v[184:185], s[10:11] offset:2560
	v_mul_f32_e32 v90, v90, v155
	v_mul_f32_e32 v91, v91, v155
	v_mul_f32_e32 v92, v92, v155
	v_mul_f32_e32 v93, v93, v155
	v_pk_fma_f32 v[90:91], v[50:51], v[90:91], v[58:59]
	v_pk_fma_f32 v[92:93], v[52:53], v[92:93], v[60:61]
	global_store_dwordx4 v131, v[90:93], s[6:7] offset:2048
	s_waitcnt vmcnt(15)
	v_pk_add_f32 v[212:213], v[212:213], 1.0 op_sel_hi:[1,0]
	v_pk_add_f32 v[214:215], v[214:215], 1.0 op_sel_hi:[1,0]
	v_pk_fma_f32 v[212:213], v[212:213], v[90:91], v[244:245]
	v_pk_fma_f32 v[214:215], v[214:215], v[92:93], v[246:247]
	v_cvt_pk_bf16_f32 v212, v212, v213
	v_cvt_pk_bf16_f32 v213, v214, v215
	global_store_dwordx2 v117, v[212:213], s[10:11] offset:3072
	v_mul_f32_e32 v94, v94, v155
	v_mul_f32_e32 v95, v95, v155
	v_mul_f32_e32 v96, v96, v155
	v_mul_f32_e32 v97, v97, v155
	v_pk_fma_f32 v[94:95], v[54:55], v[94:95], v[62:63]
	v_pk_fma_f32 v[96:97], v[56:57], v[96:97], v[64:65]
	global_store_dwordx4 v131, v[94:97], s[6:7] offset:3072
	s_waitcnt vmcnt(15)
	v_pk_add_f32 v[216:217], v[216:217], 1.0 op_sel_hi:[1,0]
	v_pk_add_f32 v[218:219], v[218:219], 1.0 op_sel_hi:[1,0]
	v_pk_fma_f32 v[216:217], v[216:217], v[94:95], v[248:249]
	v_pk_fma_f32 v[218:219], v[218:219], v[96:97], v[250:251]
	v_cvt_pk_bf16_f32 v216, v216, v217
	v_cvt_pk_bf16_f32 v217, v218, v219
	global_store_dwordx2 v117, v[216:217], s[10:11] offset:3584
	s_add_i32 s0, s68, 0x800
	s_lshl_b32 s1, s0, 13
	s_add_u32 s6, s40, s1
	s_addc_u32 s7, s41, 0
	s_lshl_b32 s1, s0, 12
	s_add_u32 s10, s44, s1
	s_addc_u32 s11, s45, 0
	s_lshr_b32 s1, s0, 11
	s_lshl_b32 s1, s1, 16
	s_add_u32 s16, s14, s1
	s_addc_u32 s17, s15, 0
	global_load_dwordx4 v[66:69], v129, s[6:7]
	global_load_dwordx4 v[70:73], v129, s[6:7] offset:1024
	global_load_dwordx4 v[74:77], v129, s[6:7] offset:2048
	global_load_dwordx4 v[78:81], v129, s[6:7] offset:3072
	global_load_dwordx4 v[82:85], v131, s[6:7]
	global_load_dwordx4 v[86:89], v131, s[6:7] offset:1024
	global_load_dwordx4 v[90:93], v131, s[6:7] offset:2048
	global_load_dwordx4 v[94:97], v131, s[6:7] offset:3072
	v_lshlrev_b32_e32 v151, 2, v116
	global_load_dwordx4 v[158:161], v151, s[16:17]
	v_lshlrev_b32_e32 v151, 2, v118
	global_load_dwordx4 v[220:223], v151, s[16:17]
	v_lshlrev_b32_e32 v151, 2, v120
	global_load_dwordx4 v[162:165], v151, s[16:17]
	v_lshlrev_b32_e32 v151, 2, v122
	global_load_dwordx4 v[224:227], v151, s[16:17]
	v_lshlrev_b32_e32 v151, 2, v124
	global_load_dwordx4 v[166:169], v151, s[16:17]
	v_lshlrev_b32_e32 v151, 2, v126
	global_load_dwordx4 v[228:231], v151, s[16:17]
	v_lshlrev_b32_e32 v151, 2, v128
	global_load_dwordx4 v[176:179], v151, s[16:17]
	v_lshlrev_b32_e32 v151, 2, v130
	global_load_dwordx4 v[232:235], v151, s[16:17]
	v_lshlrev_b32_e32 v151, 2, v132
	global_load_dwordx4 v[180:183], v151, s[16:17]
	v_lshlrev_b32_e32 v151, 2, v134
	global_load_dwordx4 v[236:239], v151, s[16:17]
	v_lshlrev_b32_e32 v151, 2, v136
	global_load_dwordx4 v[184:187], v151, s[16:17]
	v_lshlrev_b32_e32 v151, 2, v138
	global_load_dwordx4 v[240:243], v151, s[16:17]
	v_lshlrev_b32_e32 v151, 2, v140
	global_load_dwordx4 v[212:215], v151, s[16:17]
	v_lshlrev_b32_e32 v151, 2, v142
	global_load_dwordx4 v[244:247], v151, s[16:17]
	v_lshlrev_b32_e32 v151, 2, v144
	global_load_dwordx4 v[216:219], v151, s[16:17]
	v_lshlrev_b32_e32 v151, 2, v146
	global_load_dwordx4 v[248:251], v151, s[16:17]
	s_waitcnt vmcnt(23)
	v_add_f32_e32 v151, v66, v67
	v_add_f32_e32 v155, v68, v69
	v_add_f32_e32 v151, v151, v155
	v_add_f32_e32 v153, 0, v151
	s_waitcnt vmcnt(22)
	v_add_f32_e32 v151, v70, v71
	v_add_f32_e32 v155, v72, v73
	v_add_f32_e32 v151, v151, v155
	v_add_f32_e32 v153, v153, v151
	s_waitcnt vmcnt(21)
	v_add_f32_e32 v151, v74, v75
	v_add_f32_e32 v155, v76, v77
	v_add_f32_e32 v151, v151, v155
	v_add_f32_e32 v153, v153, v151
	s_waitcnt vmcnt(20)
	v_add_f32_e32 v151, v78, v79
	v_add_f32_e32 v155, v80, v81
	v_add_f32_e32 v151, v151, v155
	v_add_f32_e32 v153, v153, v151
	s_waitcnt vmcnt(19)
	v_add_f32_e32 v151, v82, v83
	v_add_f32_e32 v155, v84, v85
	v_add_f32_e32 v151, v151, v155
	v_add_f32_e32 v153, v153, v151
	s_waitcnt vmcnt(18)
	v_add_f32_e32 v151, v86, v87
	v_add_f32_e32 v155, v88, v89
	v_add_f32_e32 v151, v151, v155
	v_add_f32_e32 v153, v153, v151
	s_waitcnt vmcnt(17)
	v_add_f32_e32 v151, v90, v91
	v_add_f32_e32 v155, v92, v93
	v_add_f32_e32 v151, v151, v155
	v_add_f32_e32 v153, v153, v151
	s_waitcnt vmcnt(16)
	v_add_f32_e32 v151, v94, v95
	v_add_f32_e32 v155, v96, v97
	v_add_f32_e32 v151, v151, v155
	v_add_f32_e32 v153, v153, v151
	ds_bpermute_b32 v151, v99, v153
	s_waitcnt lgkmcnt(0)
	v_add_f32_e32 v153, v153, v151
	ds_bpermute_b32 v151, v101, v153
	s_waitcnt lgkmcnt(0)
	v_add_f32_e32 v153, v153, v151
	ds_bpermute_b32 v151, v103, v153
	s_waitcnt lgkmcnt(0)
	v_add_f32_e32 v153, v153, v151
	ds_bpermute_b32 v151, v105, v153
	s_waitcnt lgkmcnt(0)
	v_add_f32_e32 v153, v153, v151
	ds_bpermute_b32 v151, v107, v153
	s_waitcnt lgkmcnt(0)
	v_add_f32_e32 v153, v153, v151
	ds_bpermute_b32 v151, v119, v153
	s_waitcnt lgkmcnt(0)
	v_add_f32_e32 v153, v153, v151
	v_fmac_f32_e32 v66, 0xba000000, v153
	v_fmac_f32_e32 v67, 0xba000000, v153
	v_fmac_f32_e32 v68, 0xba000000, v153
	v_fmac_f32_e32 v69, 0xba000000, v153
	v_fmac_f32_e32 v70, 0xba000000, v153
	v_fmac_f32_e32 v71, 0xba000000, v153
	v_fmac_f32_e32 v72, 0xba000000, v153
	v_fmac_f32_e32 v73, 0xba000000, v153
	v_fmac_f32_e32 v74, 0xba000000, v153
	v_fmac_f32_e32 v75, 0xba000000, v153
	v_fmac_f32_e32 v76, 0xba000000, v153
	v_fmac_f32_e32 v77, 0xba000000, v153
	v_fmac_f32_e32 v78, 0xba000000, v153
	v_fmac_f32_e32 v79, 0xba000000, v153
	v_fmac_f32_e32 v80, 0xba000000, v153
	v_fmac_f32_e32 v81, 0xba000000, v153
	v_fmac_f32_e32 v82, 0xba000000, v153
	v_fmac_f32_e32 v83, 0xba000000, v153
	v_fmac_f32_e32 v84, 0xba000000, v153
	v_fmac_f32_e32 v85, 0xba000000, v153
	v_fmac_f32_e32 v86, 0xba000000, v153
	v_fmac_f32_e32 v87, 0xba000000, v153
	v_fmac_f32_e32 v88, 0xba000000, v153
	v_fmac_f32_e32 v89, 0xba000000, v153
	v_fmac_f32_e32 v90, 0xba000000, v153
	v_fmac_f32_e32 v91, 0xba000000, v153
	v_fmac_f32_e32 v92, 0xba000000, v153
	v_fmac_f32_e32 v93, 0xba000000, v153
	v_fmac_f32_e32 v94, 0xba000000, v153
	v_fmac_f32_e32 v95, 0xba000000, v153
	v_fmac_f32_e32 v96, 0xba000000, v153
	v_fmac_f32_e32 v97, 0xba000000, v153
	v_mul_f32_e32 v151, v67, v67
	v_fma_f32 v151, v66, v66, v151
	v_mul_f32_e32 v155, v69, v69
	v_fma_f32 v155, v68, v68, v155
	v_add_f32_e32 v151, v151, v155
	v_add_f32_e32 v157, 0, v151
	v_mul_f32_e32 v151, v71, v71
	v_fma_f32 v151, v70, v70, v151
	v_mul_f32_e32 v155, v73, v73
	v_fma_f32 v155, v72, v72, v155
	v_add_f32_e32 v151, v151, v155
	v_add_f32_e32 v157, v157, v151
	v_mul_f32_e32 v151, v75, v75
	v_fma_f32 v151, v74, v74, v151
	v_mul_f32_e32 v155, v77, v77
	v_fma_f32 v155, v76, v76, v155
	v_add_f32_e32 v151, v151, v155
	v_add_f32_e32 v157, v157, v151
	v_mul_f32_e32 v151, v79, v79
	v_fma_f32 v151, v78, v78, v151
	v_mul_f32_e32 v155, v81, v81
	v_fma_f32 v155, v80, v80, v155
	v_add_f32_e32 v151, v151, v155
	v_add_f32_e32 v157, v157, v151
	v_mul_f32_e32 v151, v83, v83
	v_fma_f32 v151, v82, v82, v151
	v_mul_f32_e32 v155, v85, v85
	v_fma_f32 v155, v84, v84, v155
	v_add_f32_e32 v151, v151, v155
	v_add_f32_e32 v157, v157, v151
	v_mul_f32_e32 v151, v87, v87
	v_fma_f32 v151, v86, v86, v151
	v_mul_f32_e32 v155, v89, v89
	v_fma_f32 v155, v88, v88, v155
	v_add_f32_e32 v151, v151, v155
	v_add_f32_e32 v157, v157, v151
	v_mul_f32_e32 v151, v91, v91
	v_fma_f32 v151, v90, v90, v151
	v_mul_f32_e32 v155, v93, v93
	v_fma_f32 v155, v92, v92, v155
	v_add_f32_e32 v151, v151, v155
	v_add_f32_e32 v157, v157, v151
	v_mul_f32_e32 v151, v95, v95
	v_fma_f32 v151, v94, v94, v151
	v_mul_f32_e32 v155, v97, v97
	v_fma_f32 v155, v96, v96, v155
	v_add_f32_e32 v151, v151, v155
	v_add_f32_e32 v157, v157, v151
	ds_bpermute_b32 v151, v99, v157
	s_waitcnt lgkmcnt(0)
	v_add_f32_e32 v157, v157, v151
	ds_bpermute_b32 v151, v101, v157
	s_waitcnt lgkmcnt(0)
	v_add_f32_e32 v157, v157, v151
	ds_bpermute_b32 v151, v103, v157
	s_waitcnt lgkmcnt(0)
	v_add_f32_e32 v157, v157, v151
	ds_bpermute_b32 v151, v105, v157
	s_waitcnt lgkmcnt(0)
	v_add_f32_e32 v157, v157, v151
	ds_bpermute_b32 v151, v107, v157
	s_waitcnt lgkmcnt(0)
	v_add_f32_e32 v157, v157, v151
	ds_bpermute_b32 v151, v119, v157
	s_waitcnt lgkmcnt(0)
	v_add_f32_e32 v157, v157, v151
	v_mov_b32_e32 v254, 0x3727c5ac
	v_fmamk_f32 v157, v157, 0x3a000000, v254
	v_mul_f32_e32 v151, 0x4f800000, v157
	s_mov_b32 s9, 0xf800000
	v_cmp_gt_f32_e32 vcc, s9, v157
	s_nop 1
	v_cndmask_b32_e32 v157, v157, v151, vcc
	v_sqrt_f32_e32 v151, v157
	s_nop 0
	v_add_u32_e32 v203, -1, v151
	v_fma_f32 v204, -v203, v151, v157
	v_cmp_ge_f32_e64 s[88:89], 0, v204
	v_add_u32_e32 v204, 1, v151
	s_nop 0
	v_cndmask_b32_e64 v203, v151, v203, s[88:89]
	v_fma_f32 v151, -v204, v151, v157
	v_cmp_lt_f32_e64 s[88:89], 0, v151
	s_nop 1
	v_cndmask_b32_e64 v151, v203, v204, s[88:89]
	v_mul_f32_e32 v203, 0x37800000, v151
	v_cndmask_b32_e32 v151, v151, v203, vcc
	v_mov_b32_e32 v203, 0x260
	v_cmp_class_f32_e32 vcc, v157, v203
	s_nop 1
	v_cndmask_b32_e32 v157, v151, v157, vcc
	v_div_scale_f32 v151, s[88:89], v157, v157, 1.0
	v_rcp_f32_e32 v203, v151
	s_nop 0
	v_fma_f32 v204, -v151, v203, 1.0
	v_fmac_f32_e32 v203, v204, v203
	v_div_scale_f32 v204, vcc, 1.0, v157, 1.0
	v_mul_f32_e32 v205, v204, v203
	v_fma_f32 v254, -v151, v205, v204
	v_fmac_f32_e32 v205, v254, v203
	v_fma_f32 v151, -v151, v205, v204
	v_div_fmas_f32 v151, v151, v203, v205
	v_div_fixup_f32 v155, v151, v157, 1.0
	v_mul_f32_e32 v66, v66, v155
	v_mul_f32_e32 v67, v67, v155
	v_mul_f32_e32 v68, v68, v155
	v_mul_f32_e32 v69, v69, v155
	v_pk_fma_f32 v[66:67], v[2:3], v[66:67], v[10:11]
	v_pk_fma_f32 v[68:69], v[4:5], v[68:69], v[12:13]
	global_store_dwordx4 v129, v[66:69], s[6:7]
	s_waitcnt vmcnt(15)
	v_pk_add_f32 v[158:159], v[158:159], 1.0 op_sel_hi:[1,0]
	v_pk_add_f32 v[160:161], v[160:161], 1.0 op_sel_hi:[1,0]
	v_pk_fma_f32 v[158:159], v[158:159], v[66:67], v[220:221]
	v_pk_fma_f32 v[160:161], v[160:161], v[68:69], v[222:223]
	v_cvt_pk_bf16_f32 v158, v158, v159
	v_cvt_pk_bf16_f32 v159, v160, v161
	global_store_dwordx2 v117, v[158:159], s[10:11]
	v_mul_f32_e32 v70, v70, v155
	v_mul_f32_e32 v71, v71, v155
	v_mul_f32_e32 v72, v72, v155
	v_mul_f32_e32 v73, v73, v155
	v_pk_fma_f32 v[70:71], v[6:7], v[70:71], v[14:15]
	v_pk_fma_f32 v[72:73], v[8:9], v[72:73], v[16:17]
	global_store_dwordx4 v129, v[70:73], s[6:7] offset:1024
	s_waitcnt vmcnt(15)
	v_pk_add_f32 v[162:163], v[162:163], 1.0 op_sel_hi:[1,0]
	v_pk_add_f32 v[164:165], v[164:165], 1.0 op_sel_hi:[1,0]
	v_pk_fma_f32 v[162:163], v[162:163], v[70:71], v[224:225]
	v_pk_fma_f32 v[164:165], v[164:165], v[72:73], v[226:227]
	v_cvt_pk_bf16_f32 v162, v162, v163
	v_cvt_pk_bf16_f32 v163, v164, v165
	global_store_dwordx2 v117, v[162:163], s[10:11] offset:512
	v_mul_f32_e32 v74, v74, v155
	v_mul_f32_e32 v75, v75, v155
	v_mul_f32_e32 v76, v76, v155
	v_mul_f32_e32 v77, v77, v155
	v_pk_fma_f32 v[74:75], v[18:19], v[74:75], v[26:27]
	v_pk_fma_f32 v[76:77], v[20:21], v[76:77], v[28:29]
	global_store_dwordx4 v129, v[74:77], s[6:7] offset:2048
	s_waitcnt vmcnt(15)
	v_pk_add_f32 v[166:167], v[166:167], 1.0 op_sel_hi:[1,0]
	v_pk_add_f32 v[168:169], v[168:169], 1.0 op_sel_hi:[1,0]
	v_pk_fma_f32 v[166:167], v[166:167], v[74:75], v[228:229]
	v_pk_fma_f32 v[168:169], v[168:169], v[76:77], v[230:231]
	v_cvt_pk_bf16_f32 v166, v166, v167
	v_cvt_pk_bf16_f32 v167, v168, v169
	global_store_dwordx2 v117, v[166:167], s[10:11] offset:1024
	v_mul_f32_e32 v78, v78, v155
	v_mul_f32_e32 v79, v79, v155
	v_mul_f32_e32 v80, v80, v155
	v_mul_f32_e32 v81, v81, v155
	v_pk_fma_f32 v[78:79], v[22:23], v[78:79], v[30:31]
	v_pk_fma_f32 v[80:81], v[24:25], v[80:81], v[32:33]
	global_store_dwordx4 v129, v[78:81], s[6:7] offset:3072
	s_waitcnt vmcnt(15)
	v_pk_add_f32 v[176:177], v[176:177], 1.0 op_sel_hi:[1,0]
	v_pk_add_f32 v[178:179], v[178:179], 1.0 op_sel_hi:[1,0]
	v_pk_fma_f32 v[176:177], v[176:177], v[78:79], v[232:233]
	v_pk_fma_f32 v[178:179], v[178:179], v[80:81], v[234:235]
	v_cvt_pk_bf16_f32 v176, v176, v177
	v_cvt_pk_bf16_f32 v177, v178, v179
	global_store_dwordx2 v117, v[176:177], s[10:11] offset:1536
	v_mul_f32_e32 v82, v82, v155
	v_mul_f32_e32 v83, v83, v155
	v_mul_f32_e32 v84, v84, v155
	v_mul_f32_e32 v85, v85, v155
	v_pk_fma_f32 v[82:83], v[34:35], v[82:83], v[42:43]
	v_pk_fma_f32 v[84:85], v[36:37], v[84:85], v[44:45]
	global_store_dwordx4 v131, v[82:85], s[6:7]
	s_waitcnt vmcnt(15)
	v_pk_add_f32 v[180:181], v[180:181], 1.0 op_sel_hi:[1,0]
	v_pk_add_f32 v[182:183], v[182:183], 1.0 op_sel_hi:[1,0]
	v_pk_fma_f32 v[180:181], v[180:181], v[82:83], v[236:237]
	v_pk_fma_f32 v[182:183], v[182:183], v[84:85], v[238:239]
	v_cvt_pk_bf16_f32 v180, v180, v181
	v_cvt_pk_bf16_f32 v181, v182, v183
	global_store_dwordx2 v117, v[180:181], s[10:11] offset:2048
	v_mul_f32_e32 v86, v86, v155
	v_mul_f32_e32 v87, v87, v155
	v_mul_f32_e32 v88, v88, v155
	v_mul_f32_e32 v89, v89, v155
	v_pk_fma_f32 v[86:87], v[38:39], v[86:87], v[46:47]
	v_pk_fma_f32 v[88:89], v[40:41], v[88:89], v[48:49]
	global_store_dwordx4 v131, v[86:89], s[6:7] offset:1024
	s_waitcnt vmcnt(15)
	v_pk_add_f32 v[184:185], v[184:185], 1.0 op_sel_hi:[1,0]
	v_pk_add_f32 v[186:187], v[186:187], 1.0 op_sel_hi:[1,0]
	v_pk_fma_f32 v[184:185], v[184:185], v[86:87], v[240:241]
	v_pk_fma_f32 v[186:187], v[186:187], v[88:89], v[242:243]
	v_cvt_pk_bf16_f32 v184, v184, v185
	v_cvt_pk_bf16_f32 v185, v186, v187
	global_store_dwordx2 v117, v[184:185], s[10:11] offset:2560
	v_mul_f32_e32 v90, v90, v155
	v_mul_f32_e32 v91, v91, v155
	v_mul_f32_e32 v92, v92, v155
	v_mul_f32_e32 v93, v93, v155
	v_pk_fma_f32 v[90:91], v[50:51], v[90:91], v[58:59]
	v_pk_fma_f32 v[92:93], v[52:53], v[92:93], v[60:61]
	global_store_dwordx4 v131, v[90:93], s[6:7] offset:2048
	s_waitcnt vmcnt(15)
	v_pk_add_f32 v[212:213], v[212:213], 1.0 op_sel_hi:[1,0]
	v_pk_add_f32 v[214:215], v[214:215], 1.0 op_sel_hi:[1,0]
	v_pk_fma_f32 v[212:213], v[212:213], v[90:91], v[244:245]
	v_pk_fma_f32 v[214:215], v[214:215], v[92:93], v[246:247]
	v_cvt_pk_bf16_f32 v212, v212, v213
	v_cvt_pk_bf16_f32 v213, v214, v215
	global_store_dwordx2 v117, v[212:213], s[10:11] offset:3072
	v_mul_f32_e32 v94, v94, v155
	v_mul_f32_e32 v95, v95, v155
	v_mul_f32_e32 v96, v96, v155
	v_mul_f32_e32 v97, v97, v155
	v_pk_fma_f32 v[94:95], v[54:55], v[94:95], v[62:63]
	v_pk_fma_f32 v[96:97], v[56:57], v[96:97], v[64:65]
	global_store_dwordx4 v131, v[94:97], s[6:7] offset:3072
	s_waitcnt vmcnt(15)
	v_pk_add_f32 v[216:217], v[216:217], 1.0 op_sel_hi:[1,0]
	v_pk_add_f32 v[218:219], v[218:219], 1.0 op_sel_hi:[1,0]
	v_pk_fma_f32 v[216:217], v[216:217], v[94:95], v[248:249]
	v_pk_fma_f32 v[218:219], v[218:219], v[96:97], v[250:251]
	v_cvt_pk_bf16_f32 v216, v216, v217
	v_cvt_pk_bf16_f32 v217, v218, v219
	global_store_dwordx2 v117, v[216:217], s[10:11] offset:3584
	s_add_i32 s0, s68, 0x1000
	s_lshl_b32 s1, s0, 13
	s_add_u32 s6, s40, s1
	s_addc_u32 s7, s41, 0
	s_lshl_b32 s1, s0, 12
	s_add_u32 s10, s44, s1
	s_addc_u32 s11, s45, 0
	s_lshr_b32 s1, s0, 11
	s_lshl_b32 s1, s1, 16
	s_add_u32 s16, s14, s1
	s_addc_u32 s17, s15, 0
	global_load_dwordx4 v[66:69], v129, s[6:7]
	global_load_dwordx4 v[70:73], v129, s[6:7] offset:1024
	global_load_dwordx4 v[74:77], v129, s[6:7] offset:2048
	global_load_dwordx4 v[78:81], v129, s[6:7] offset:3072
	global_load_dwordx4 v[82:85], v131, s[6:7]
	global_load_dwordx4 v[86:89], v131, s[6:7] offset:1024
	global_load_dwordx4 v[90:93], v131, s[6:7] offset:2048
	global_load_dwordx4 v[94:97], v131, s[6:7] offset:3072
	v_lshlrev_b32_e32 v151, 2, v116
	global_load_dwordx4 v[158:161], v151, s[16:17]
	v_lshlrev_b32_e32 v151, 2, v118
	global_load_dwordx4 v[220:223], v151, s[16:17]
	v_lshlrev_b32_e32 v151, 2, v120
	global_load_dwordx4 v[162:165], v151, s[16:17]
	v_lshlrev_b32_e32 v151, 2, v122
	global_load_dwordx4 v[224:227], v151, s[16:17]
	v_lshlrev_b32_e32 v151, 2, v124
	global_load_dwordx4 v[166:169], v151, s[16:17]
	v_lshlrev_b32_e32 v151, 2, v126
	global_load_dwordx4 v[228:231], v151, s[16:17]
	v_lshlrev_b32_e32 v151, 2, v128
	global_load_dwordx4 v[176:179], v151, s[16:17]
	v_lshlrev_b32_e32 v151, 2, v130
	global_load_dwordx4 v[232:235], v151, s[16:17]
	v_lshlrev_b32_e32 v151, 2, v132
	global_load_dwordx4 v[180:183], v151, s[16:17]
	v_lshlrev_b32_e32 v151, 2, v134
	global_load_dwordx4 v[236:239], v151, s[16:17]
	v_lshlrev_b32_e32 v151, 2, v136
	global_load_dwordx4 v[184:187], v151, s[16:17]
	v_lshlrev_b32_e32 v151, 2, v138
	global_load_dwordx4 v[240:243], v151, s[16:17]
	v_lshlrev_b32_e32 v151, 2, v140
	global_load_dwordx4 v[212:215], v151, s[16:17]
	v_lshlrev_b32_e32 v151, 2, v142
	global_load_dwordx4 v[244:247], v151, s[16:17]
	v_lshlrev_b32_e32 v151, 2, v144
	global_load_dwordx4 v[216:219], v151, s[16:17]
	v_lshlrev_b32_e32 v151, 2, v146
	global_load_dwordx4 v[248:251], v151, s[16:17]
	s_waitcnt vmcnt(23)
	v_add_f32_e32 v151, v66, v67
	v_add_f32_e32 v155, v68, v69
	v_add_f32_e32 v151, v151, v155
	v_add_f32_e32 v153, 0, v151
	s_waitcnt vmcnt(22)
	v_add_f32_e32 v151, v70, v71
	v_add_f32_e32 v155, v72, v73
	v_add_f32_e32 v151, v151, v155
	v_add_f32_e32 v153, v153, v151
	s_waitcnt vmcnt(21)
	v_add_f32_e32 v151, v74, v75
	v_add_f32_e32 v155, v76, v77
	v_add_f32_e32 v151, v151, v155
	v_add_f32_e32 v153, v153, v151
	s_waitcnt vmcnt(20)
	v_add_f32_e32 v151, v78, v79
	v_add_f32_e32 v155, v80, v81
	v_add_f32_e32 v151, v151, v155
	v_add_f32_e32 v153, v153, v151
	s_waitcnt vmcnt(19)
	v_add_f32_e32 v151, v82, v83
	v_add_f32_e32 v155, v84, v85
	v_add_f32_e32 v151, v151, v155
	v_add_f32_e32 v153, v153, v151
	s_waitcnt vmcnt(18)
	v_add_f32_e32 v151, v86, v87
	v_add_f32_e32 v155, v88, v89
	v_add_f32_e32 v151, v151, v155
	v_add_f32_e32 v153, v153, v151
	s_waitcnt vmcnt(17)
	v_add_f32_e32 v151, v90, v91
	v_add_f32_e32 v155, v92, v93
	v_add_f32_e32 v151, v151, v155
	v_add_f32_e32 v153, v153, v151
	s_waitcnt vmcnt(16)
	v_add_f32_e32 v151, v94, v95
	v_add_f32_e32 v155, v96, v97
	v_add_f32_e32 v151, v151, v155
	v_add_f32_e32 v153, v153, v151
	ds_bpermute_b32 v151, v99, v153
	s_waitcnt lgkmcnt(0)
	v_add_f32_e32 v153, v153, v151
	ds_bpermute_b32 v151, v101, v153
	s_waitcnt lgkmcnt(0)
	v_add_f32_e32 v153, v153, v151
	ds_bpermute_b32 v151, v103, v153
	s_waitcnt lgkmcnt(0)
	v_add_f32_e32 v153, v153, v151
	ds_bpermute_b32 v151, v105, v153
	s_waitcnt lgkmcnt(0)
	v_add_f32_e32 v153, v153, v151
	ds_bpermute_b32 v151, v107, v153
	s_waitcnt lgkmcnt(0)
	v_add_f32_e32 v153, v153, v151
	ds_bpermute_b32 v151, v119, v153
	s_waitcnt lgkmcnt(0)
	v_add_f32_e32 v153, v153, v151
	v_fmac_f32_e32 v66, 0xba000000, v153
	v_fmac_f32_e32 v67, 0xba000000, v153
	v_fmac_f32_e32 v68, 0xba000000, v153
	v_fmac_f32_e32 v69, 0xba000000, v153
	v_fmac_f32_e32 v70, 0xba000000, v153
	v_fmac_f32_e32 v71, 0xba000000, v153
	v_fmac_f32_e32 v72, 0xba000000, v153
	v_fmac_f32_e32 v73, 0xba000000, v153
	v_fmac_f32_e32 v74, 0xba000000, v153
	v_fmac_f32_e32 v75, 0xba000000, v153
	v_fmac_f32_e32 v76, 0xba000000, v153
	v_fmac_f32_e32 v77, 0xba000000, v153
	v_fmac_f32_e32 v78, 0xba000000, v153
	v_fmac_f32_e32 v79, 0xba000000, v153
	v_fmac_f32_e32 v80, 0xba000000, v153
	v_fmac_f32_e32 v81, 0xba000000, v153
	v_fmac_f32_e32 v82, 0xba000000, v153
	v_fmac_f32_e32 v83, 0xba000000, v153
	v_fmac_f32_e32 v84, 0xba000000, v153
	v_fmac_f32_e32 v85, 0xba000000, v153
	v_fmac_f32_e32 v86, 0xba000000, v153
	v_fmac_f32_e32 v87, 0xba000000, v153
	v_fmac_f32_e32 v88, 0xba000000, v153
	v_fmac_f32_e32 v89, 0xba000000, v153
	v_fmac_f32_e32 v90, 0xba000000, v153
	v_fmac_f32_e32 v91, 0xba000000, v153
	v_fmac_f32_e32 v92, 0xba000000, v153
	v_fmac_f32_e32 v93, 0xba000000, v153
	v_fmac_f32_e32 v94, 0xba000000, v153
	v_fmac_f32_e32 v95, 0xba000000, v153
	v_fmac_f32_e32 v96, 0xba000000, v153
	v_fmac_f32_e32 v97, 0xba000000, v153
	v_mul_f32_e32 v151, v67, v67
	v_fma_f32 v151, v66, v66, v151
	v_mul_f32_e32 v155, v69, v69
	v_fma_f32 v155, v68, v68, v155
	v_add_f32_e32 v151, v151, v155
	v_add_f32_e32 v157, 0, v151
	v_mul_f32_e32 v151, v71, v71
	v_fma_f32 v151, v70, v70, v151
	v_mul_f32_e32 v155, v73, v73
	v_fma_f32 v155, v72, v72, v155
	v_add_f32_e32 v151, v151, v155
	v_add_f32_e32 v157, v157, v151
	v_mul_f32_e32 v151, v75, v75
	v_fma_f32 v151, v74, v74, v151
	v_mul_f32_e32 v155, v77, v77
	v_fma_f32 v155, v76, v76, v155
	v_add_f32_e32 v151, v151, v155
	v_add_f32_e32 v157, v157, v151
	v_mul_f32_e32 v151, v79, v79
	v_fma_f32 v151, v78, v78, v151
	v_mul_f32_e32 v155, v81, v81
	v_fma_f32 v155, v80, v80, v155
	v_add_f32_e32 v151, v151, v155
	v_add_f32_e32 v157, v157, v151
	v_mul_f32_e32 v151, v83, v83
	v_fma_f32 v151, v82, v82, v151
	v_mul_f32_e32 v155, v85, v85
	v_fma_f32 v155, v84, v84, v155
	v_add_f32_e32 v151, v151, v155
	v_add_f32_e32 v157, v157, v151
	v_mul_f32_e32 v151, v87, v87
	v_fma_f32 v151, v86, v86, v151
	v_mul_f32_e32 v155, v89, v89
	v_fma_f32 v155, v88, v88, v155
	v_add_f32_e32 v151, v151, v155
	v_add_f32_e32 v157, v157, v151
	v_mul_f32_e32 v151, v91, v91
	v_fma_f32 v151, v90, v90, v151
	v_mul_f32_e32 v155, v93, v93
	v_fma_f32 v155, v92, v92, v155
	v_add_f32_e32 v151, v151, v155
	v_add_f32_e32 v157, v157, v151
	v_mul_f32_e32 v151, v95, v95
	v_fma_f32 v151, v94, v94, v151
	v_mul_f32_e32 v155, v97, v97
	v_fma_f32 v155, v96, v96, v155
	v_add_f32_e32 v151, v151, v155
	v_add_f32_e32 v157, v157, v151
	ds_bpermute_b32 v151, v99, v157
	s_waitcnt lgkmcnt(0)
	v_add_f32_e32 v157, v157, v151
	ds_bpermute_b32 v151, v101, v157
	s_waitcnt lgkmcnt(0)
	v_add_f32_e32 v157, v157, v151
	ds_bpermute_b32 v151, v103, v157
	s_waitcnt lgkmcnt(0)
	v_add_f32_e32 v157, v157, v151
	ds_bpermute_b32 v151, v105, v157
	s_waitcnt lgkmcnt(0)
	v_add_f32_e32 v157, v157, v151
	ds_bpermute_b32 v151, v107, v157
	s_waitcnt lgkmcnt(0)
	v_add_f32_e32 v157, v157, v151
	ds_bpermute_b32 v151, v119, v157
	s_waitcnt lgkmcnt(0)
	v_add_f32_e32 v157, v157, v151
	v_mov_b32_e32 v254, 0x3727c5ac
	v_fmamk_f32 v157, v157, 0x3a000000, v254
	v_mul_f32_e32 v151, 0x4f800000, v157
	s_mov_b32 s9, 0xf800000
	v_cmp_gt_f32_e32 vcc, s9, v157
	s_nop 1
	v_cndmask_b32_e32 v157, v157, v151, vcc
	v_sqrt_f32_e32 v151, v157
	s_nop 0
	v_add_u32_e32 v203, -1, v151
	v_fma_f32 v204, -v203, v151, v157
	v_cmp_ge_f32_e64 s[88:89], 0, v204
	v_add_u32_e32 v204, 1, v151
	s_nop 0
	v_cndmask_b32_e64 v203, v151, v203, s[88:89]
	v_fma_f32 v151, -v204, v151, v157
	v_cmp_lt_f32_e64 s[88:89], 0, v151
	s_nop 1
	v_cndmask_b32_e64 v151, v203, v204, s[88:89]
	v_mul_f32_e32 v203, 0x37800000, v151
	v_cndmask_b32_e32 v151, v151, v203, vcc
	v_mov_b32_e32 v203, 0x260
	v_cmp_class_f32_e32 vcc, v157, v203
	s_nop 1
	v_cndmask_b32_e32 v157, v151, v157, vcc
	v_div_scale_f32 v151, s[88:89], v157, v157, 1.0
	v_rcp_f32_e32 v203, v151
	s_nop 0
	v_fma_f32 v204, -v151, v203, 1.0
	v_fmac_f32_e32 v203, v204, v203
	v_div_scale_f32 v204, vcc, 1.0, v157, 1.0
	v_mul_f32_e32 v205, v204, v203
	v_fma_f32 v254, -v151, v205, v204
	v_fmac_f32_e32 v205, v254, v203
	v_fma_f32 v151, -v151, v205, v204
	v_div_fmas_f32 v151, v151, v203, v205
	v_div_fixup_f32 v155, v151, v157, 1.0
	v_mul_f32_e32 v66, v66, v155
	v_mul_f32_e32 v67, v67, v155
	v_mul_f32_e32 v68, v68, v155
	v_mul_f32_e32 v69, v69, v155
	v_pk_fma_f32 v[66:67], v[2:3], v[66:67], v[10:11]
	v_pk_fma_f32 v[68:69], v[4:5], v[68:69], v[12:13]
	global_store_dwordx4 v129, v[66:69], s[6:7]
	s_waitcnt vmcnt(15)
	v_pk_add_f32 v[158:159], v[158:159], 1.0 op_sel_hi:[1,0]
	v_pk_add_f32 v[160:161], v[160:161], 1.0 op_sel_hi:[1,0]
	v_pk_fma_f32 v[158:159], v[158:159], v[66:67], v[220:221]
	v_pk_fma_f32 v[160:161], v[160:161], v[68:69], v[222:223]
	v_cvt_pk_bf16_f32 v158, v158, v159
	v_cvt_pk_bf16_f32 v159, v160, v161
	global_store_dwordx2 v117, v[158:159], s[10:11]
	v_mul_f32_e32 v70, v70, v155
	v_mul_f32_e32 v71, v71, v155
	v_mul_f32_e32 v72, v72, v155
	v_mul_f32_e32 v73, v73, v155
	v_pk_fma_f32 v[70:71], v[6:7], v[70:71], v[14:15]
	v_pk_fma_f32 v[72:73], v[8:9], v[72:73], v[16:17]
	global_store_dwordx4 v129, v[70:73], s[6:7] offset:1024
	s_waitcnt vmcnt(15)
	v_pk_add_f32 v[162:163], v[162:163], 1.0 op_sel_hi:[1,0]
	v_pk_add_f32 v[164:165], v[164:165], 1.0 op_sel_hi:[1,0]
	v_pk_fma_f32 v[162:163], v[162:163], v[70:71], v[224:225]
	v_pk_fma_f32 v[164:165], v[164:165], v[72:73], v[226:227]
	v_cvt_pk_bf16_f32 v162, v162, v163
	v_cvt_pk_bf16_f32 v163, v164, v165
	global_store_dwordx2 v117, v[162:163], s[10:11] offset:512
	v_mul_f32_e32 v74, v74, v155
	v_mul_f32_e32 v75, v75, v155
	v_mul_f32_e32 v76, v76, v155
	v_mul_f32_e32 v77, v77, v155
	v_pk_fma_f32 v[74:75], v[18:19], v[74:75], v[26:27]
	v_pk_fma_f32 v[76:77], v[20:21], v[76:77], v[28:29]
	global_store_dwordx4 v129, v[74:77], s[6:7] offset:2048
	s_waitcnt vmcnt(15)
	v_pk_add_f32 v[166:167], v[166:167], 1.0 op_sel_hi:[1,0]
	v_pk_add_f32 v[168:169], v[168:169], 1.0 op_sel_hi:[1,0]
	v_pk_fma_f32 v[166:167], v[166:167], v[74:75], v[228:229]
	v_pk_fma_f32 v[168:169], v[168:169], v[76:77], v[230:231]
	v_cvt_pk_bf16_f32 v166, v166, v167
	v_cvt_pk_bf16_f32 v167, v168, v169
	global_store_dwordx2 v117, v[166:167], s[10:11] offset:1024
	v_mul_f32_e32 v78, v78, v155
	v_mul_f32_e32 v79, v79, v155
	v_mul_f32_e32 v80, v80, v155
	v_mul_f32_e32 v81, v81, v155
	v_pk_fma_f32 v[78:79], v[22:23], v[78:79], v[30:31]
	v_pk_fma_f32 v[80:81], v[24:25], v[80:81], v[32:33]
	global_store_dwordx4 v129, v[78:81], s[6:7] offset:3072
	s_waitcnt vmcnt(15)
	v_pk_add_f32 v[176:177], v[176:177], 1.0 op_sel_hi:[1,0]
	v_pk_add_f32 v[178:179], v[178:179], 1.0 op_sel_hi:[1,0]
	v_pk_fma_f32 v[176:177], v[176:177], v[78:79], v[232:233]
	v_pk_fma_f32 v[178:179], v[178:179], v[80:81], v[234:235]
	v_cvt_pk_bf16_f32 v176, v176, v177
	v_cvt_pk_bf16_f32 v177, v178, v179
	global_store_dwordx2 v117, v[176:177], s[10:11] offset:1536
	v_mul_f32_e32 v82, v82, v155
	v_mul_f32_e32 v83, v83, v155
	v_mul_f32_e32 v84, v84, v155
	v_mul_f32_e32 v85, v85, v155
	v_pk_fma_f32 v[82:83], v[34:35], v[82:83], v[42:43]
	v_pk_fma_f32 v[84:85], v[36:37], v[84:85], v[44:45]
	global_store_dwordx4 v131, v[82:85], s[6:7]
	s_waitcnt vmcnt(15)
	v_pk_add_f32 v[180:181], v[180:181], 1.0 op_sel_hi:[1,0]
	v_pk_add_f32 v[182:183], v[182:183], 1.0 op_sel_hi:[1,0]
	v_pk_fma_f32 v[180:181], v[180:181], v[82:83], v[236:237]
	v_pk_fma_f32 v[182:183], v[182:183], v[84:85], v[238:239]
	v_cvt_pk_bf16_f32 v180, v180, v181
	v_cvt_pk_bf16_f32 v181, v182, v183
	global_store_dwordx2 v117, v[180:181], s[10:11] offset:2048
	v_mul_f32_e32 v86, v86, v155
	v_mul_f32_e32 v87, v87, v155
	v_mul_f32_e32 v88, v88, v155
	v_mul_f32_e32 v89, v89, v155
	v_pk_fma_f32 v[86:87], v[38:39], v[86:87], v[46:47]
	v_pk_fma_f32 v[88:89], v[40:41], v[88:89], v[48:49]
	global_store_dwordx4 v131, v[86:89], s[6:7] offset:1024
	s_waitcnt vmcnt(15)
	v_pk_add_f32 v[184:185], v[184:185], 1.0 op_sel_hi:[1,0]
	v_pk_add_f32 v[186:187], v[186:187], 1.0 op_sel_hi:[1,0]
	v_pk_fma_f32 v[184:185], v[184:185], v[86:87], v[240:241]
	v_pk_fma_f32 v[186:187], v[186:187], v[88:89], v[242:243]
	v_cvt_pk_bf16_f32 v184, v184, v185
	v_cvt_pk_bf16_f32 v185, v186, v187
	global_store_dwordx2 v117, v[184:185], s[10:11] offset:2560
	v_mul_f32_e32 v90, v90, v155
	v_mul_f32_e32 v91, v91, v155
	v_mul_f32_e32 v92, v92, v155
	v_mul_f32_e32 v93, v93, v155
	v_pk_fma_f32 v[90:91], v[50:51], v[90:91], v[58:59]
	v_pk_fma_f32 v[92:93], v[52:53], v[92:93], v[60:61]
	global_store_dwordx4 v131, v[90:93], s[6:7] offset:2048
	s_waitcnt vmcnt(15)
	v_pk_add_f32 v[212:213], v[212:213], 1.0 op_sel_hi:[1,0]
	v_pk_add_f32 v[214:215], v[214:215], 1.0 op_sel_hi:[1,0]
	v_pk_fma_f32 v[212:213], v[212:213], v[90:91], v[244:245]
	v_pk_fma_f32 v[214:215], v[214:215], v[92:93], v[246:247]
	v_cvt_pk_bf16_f32 v212, v212, v213
	v_cvt_pk_bf16_f32 v213, v214, v215
	global_store_dwordx2 v117, v[212:213], s[10:11] offset:3072
	v_mul_f32_e32 v94, v94, v155
	v_mul_f32_e32 v95, v95, v155
	v_mul_f32_e32 v96, v96, v155
	v_mul_f32_e32 v97, v97, v155
	v_pk_fma_f32 v[94:95], v[54:55], v[94:95], v[62:63]
	v_pk_fma_f32 v[96:97], v[56:57], v[96:97], v[64:65]
	global_store_dwordx4 v131, v[94:97], s[6:7] offset:3072
	s_waitcnt vmcnt(15)
	v_pk_add_f32 v[216:217], v[216:217], 1.0 op_sel_hi:[1,0]
	v_pk_add_f32 v[218:219], v[218:219], 1.0 op_sel_hi:[1,0]
	v_pk_fma_f32 v[216:217], v[216:217], v[94:95], v[248:249]
	v_pk_fma_f32 v[218:219], v[218:219], v[96:97], v[250:251]
	v_cvt_pk_bf16_f32 v216, v216, v217
	v_cvt_pk_bf16_f32 v217, v218, v219
	global_store_dwordx2 v117, v[216:217], s[10:11] offset:3584
	s_mov_b32 s0, s72
	s_cmpk_gt_u32 s72, 0x1fff
	s_cbranch_scc1 .Lp6_r3_sample
	s_lshl_b32 s1, s0, 13
	s_add_u32 s6, s40, s1
	s_addc_u32 s7, s41, 0
	s_lshl_b32 s1, s0, 12
	s_add_u32 s10, s44, s1
	s_addc_u32 s11, s45, 0
	s_lshr_b32 s1, s0, 11
	s_lshl_b32 s1, s1, 16
	s_add_u32 s16, s14, s1
	s_addc_u32 s17, s15, 0
	global_load_dwordx4 v[66:69], v129, s[6:7]
	global_load_dwordx4 v[70:73], v129, s[6:7] offset:1024
	global_load_dwordx4 v[74:77], v129, s[6:7] offset:2048
	global_load_dwordx4 v[78:81], v129, s[6:7] offset:3072
	global_load_dwordx4 v[82:85], v131, s[6:7]
	global_load_dwordx4 v[86:89], v131, s[6:7] offset:1024
	global_load_dwordx4 v[90:93], v131, s[6:7] offset:2048
	global_load_dwordx4 v[94:97], v131, s[6:7] offset:3072
	v_lshlrev_b32_e32 v151, 2, v116
	global_load_dwordx4 v[158:161], v151, s[16:17]
	v_lshlrev_b32_e32 v151, 2, v118
	global_load_dwordx4 v[220:223], v151, s[16:17]
	v_lshlrev_b32_e32 v151, 2, v120
	global_load_dwordx4 v[162:165], v151, s[16:17]
	v_lshlrev_b32_e32 v151, 2, v122
	global_load_dwordx4 v[224:227], v151, s[16:17]
	v_lshlrev_b32_e32 v151, 2, v124
	global_load_dwordx4 v[166:169], v151, s[16:17]
	v_lshlrev_b32_e32 v151, 2, v126
	global_load_dwordx4 v[228:231], v151, s[16:17]
	v_lshlrev_b32_e32 v151, 2, v128
	global_load_dwordx4 v[176:179], v151, s[16:17]
	v_lshlrev_b32_e32 v151, 2, v130
	global_load_dwordx4 v[232:235], v151, s[16:17]
	v_lshlrev_b32_e32 v151, 2, v132
	global_load_dwordx4 v[180:183], v151, s[16:17]
	v_lshlrev_b32_e32 v151, 2, v134
	global_load_dwordx4 v[236:239], v151, s[16:17]
	v_lshlrev_b32_e32 v151, 2, v136
	global_load_dwordx4 v[184:187], v151, s[16:17]
	v_lshlrev_b32_e32 v151, 2, v138
	global_load_dwordx4 v[240:243], v151, s[16:17]
	v_lshlrev_b32_e32 v151, 2, v140
	global_load_dwordx4 v[212:215], v151, s[16:17]
	v_lshlrev_b32_e32 v151, 2, v142
	global_load_dwordx4 v[244:247], v151, s[16:17]
	v_lshlrev_b32_e32 v151, 2, v144
	global_load_dwordx4 v[216:219], v151, s[16:17]
	v_lshlrev_b32_e32 v151, 2, v146
	global_load_dwordx4 v[248:251], v151, s[16:17]
	s_waitcnt vmcnt(23)
	v_add_f32_e32 v151, v66, v67
	v_add_f32_e32 v155, v68, v69
	v_add_f32_e32 v151, v151, v155
	v_add_f32_e32 v153, 0, v151
	s_waitcnt vmcnt(22)
	v_add_f32_e32 v151, v70, v71
	v_add_f32_e32 v155, v72, v73
	v_add_f32_e32 v151, v151, v155
	v_add_f32_e32 v153, v153, v151
	s_waitcnt vmcnt(21)
	v_add_f32_e32 v151, v74, v75
	v_add_f32_e32 v155, v76, v77
	v_add_f32_e32 v151, v151, v155
	v_add_f32_e32 v153, v153, v151
	s_waitcnt vmcnt(20)
	v_add_f32_e32 v151, v78, v79
	v_add_f32_e32 v155, v80, v81
	v_add_f32_e32 v151, v151, v155
	v_add_f32_e32 v153, v153, v151
	s_waitcnt vmcnt(19)
	v_add_f32_e32 v151, v82, v83
	v_add_f32_e32 v155, v84, v85
	v_add_f32_e32 v151, v151, v155
	v_add_f32_e32 v153, v153, v151
	s_waitcnt vmcnt(18)
	v_add_f32_e32 v151, v86, v87
	v_add_f32_e32 v155, v88, v89
	v_add_f32_e32 v151, v151, v155
	v_add_f32_e32 v153, v153, v151
	s_waitcnt vmcnt(17)
	v_add_f32_e32 v151, v90, v91
	v_add_f32_e32 v155, v92, v93
	v_add_f32_e32 v151, v151, v155
	v_add_f32_e32 v153, v153, v151
	s_waitcnt vmcnt(16)
	v_add_f32_e32 v151, v94, v95
	v_add_f32_e32 v155, v96, v97
	v_add_f32_e32 v151, v151, v155
	v_add_f32_e32 v153, v153, v151
	ds_bpermute_b32 v151, v99, v153
	s_waitcnt lgkmcnt(0)
	v_add_f32_e32 v153, v153, v151
	ds_bpermute_b32 v151, v101, v153
	s_waitcnt lgkmcnt(0)
	v_add_f32_e32 v153, v153, v151
	ds_bpermute_b32 v151, v103, v153
	s_waitcnt lgkmcnt(0)
	v_add_f32_e32 v153, v153, v151
	ds_bpermute_b32 v151, v105, v153
	s_waitcnt lgkmcnt(0)
	v_add_f32_e32 v153, v153, v151
	ds_bpermute_b32 v151, v107, v153
	s_waitcnt lgkmcnt(0)
	v_add_f32_e32 v153, v153, v151
	ds_bpermute_b32 v151, v119, v153
	s_waitcnt lgkmcnt(0)
	v_add_f32_e32 v153, v153, v151
	v_fmac_f32_e32 v66, 0xba000000, v153
	v_fmac_f32_e32 v67, 0xba000000, v153
	v_fmac_f32_e32 v68, 0xba000000, v153
	v_fmac_f32_e32 v69, 0xba000000, v153
	v_fmac_f32_e32 v70, 0xba000000, v153
	v_fmac_f32_e32 v71, 0xba000000, v153
	v_fmac_f32_e32 v72, 0xba000000, v153
	v_fmac_f32_e32 v73, 0xba000000, v153
	v_fmac_f32_e32 v74, 0xba000000, v153
	v_fmac_f32_e32 v75, 0xba000000, v153
	v_fmac_f32_e32 v76, 0xba000000, v153
	v_fmac_f32_e32 v77, 0xba000000, v153
	v_fmac_f32_e32 v78, 0xba000000, v153
	v_fmac_f32_e32 v79, 0xba000000, v153
	v_fmac_f32_e32 v80, 0xba000000, v153
	v_fmac_f32_e32 v81, 0xba000000, v153
	v_fmac_f32_e32 v82, 0xba000000, v153
	v_fmac_f32_e32 v83, 0xba000000, v153
	v_fmac_f32_e32 v84, 0xba000000, v153
	v_fmac_f32_e32 v85, 0xba000000, v153
	v_fmac_f32_e32 v86, 0xba000000, v153
	v_fmac_f32_e32 v87, 0xba000000, v153
	v_fmac_f32_e32 v88, 0xba000000, v153
	v_fmac_f32_e32 v89, 0xba000000, v153
	v_fmac_f32_e32 v90, 0xba000000, v153
	v_fmac_f32_e32 v91, 0xba000000, v153
	v_fmac_f32_e32 v92, 0xba000000, v153
	v_fmac_f32_e32 v93, 0xba000000, v153
	v_fmac_f32_e32 v94, 0xba000000, v153
	v_fmac_f32_e32 v95, 0xba000000, v153
	v_fmac_f32_e32 v96, 0xba000000, v153
	v_fmac_f32_e32 v97, 0xba000000, v153
	v_mul_f32_e32 v151, v67, v67
	v_fma_f32 v151, v66, v66, v151
	v_mul_f32_e32 v155, v69, v69
	v_fma_f32 v155, v68, v68, v155
	v_add_f32_e32 v151, v151, v155
	v_add_f32_e32 v157, 0, v151
	v_mul_f32_e32 v151, v71, v71
	v_fma_f32 v151, v70, v70, v151
	v_mul_f32_e32 v155, v73, v73
	v_fma_f32 v155, v72, v72, v155
	v_add_f32_e32 v151, v151, v155
	v_add_f32_e32 v157, v157, v151
	v_mul_f32_e32 v151, v75, v75
	v_fma_f32 v151, v74, v74, v151
	v_mul_f32_e32 v155, v77, v77
	v_fma_f32 v155, v76, v76, v155
	v_add_f32_e32 v151, v151, v155
	v_add_f32_e32 v157, v157, v151
	v_mul_f32_e32 v151, v79, v79
	v_fma_f32 v151, v78, v78, v151
	v_mul_f32_e32 v155, v81, v81
	v_fma_f32 v155, v80, v80, v155
	v_add_f32_e32 v151, v151, v155
	v_add_f32_e32 v157, v157, v151
	v_mul_f32_e32 v151, v83, v83
	v_fma_f32 v151, v82, v82, v151
	v_mul_f32_e32 v155, v85, v85
	v_fma_f32 v155, v84, v84, v155
	v_add_f32_e32 v151, v151, v155
	v_add_f32_e32 v157, v157, v151
	v_mul_f32_e32 v151, v87, v87
	v_fma_f32 v151, v86, v86, v151
	v_mul_f32_e32 v155, v89, v89
	v_fma_f32 v155, v88, v88, v155
	v_add_f32_e32 v151, v151, v155
	v_add_f32_e32 v157, v157, v151
	v_mul_f32_e32 v151, v91, v91
	v_fma_f32 v151, v90, v90, v151
	v_mul_f32_e32 v155, v93, v93
	v_fma_f32 v155, v92, v92, v155
	v_add_f32_e32 v151, v151, v155
	v_add_f32_e32 v157, v157, v151
	v_mul_f32_e32 v151, v95, v95
	v_fma_f32 v151, v94, v94, v151
	v_mul_f32_e32 v155, v97, v97
	v_fma_f32 v155, v96, v96, v155
	v_add_f32_e32 v151, v151, v155
	v_add_f32_e32 v157, v157, v151
	ds_bpermute_b32 v151, v99, v157
	s_waitcnt lgkmcnt(0)
	v_add_f32_e32 v157, v157, v151
	ds_bpermute_b32 v151, v101, v157
	s_waitcnt lgkmcnt(0)
	v_add_f32_e32 v157, v157, v151
	ds_bpermute_b32 v151, v103, v157
	s_waitcnt lgkmcnt(0)
	v_add_f32_e32 v157, v157, v151
	ds_bpermute_b32 v151, v105, v157
	s_waitcnt lgkmcnt(0)
	v_add_f32_e32 v157, v157, v151
	ds_bpermute_b32 v151, v107, v157
	s_waitcnt lgkmcnt(0)
	v_add_f32_e32 v157, v157, v151
	ds_bpermute_b32 v151, v119, v157
	s_waitcnt lgkmcnt(0)
	v_add_f32_e32 v157, v157, v151
	v_mov_b32_e32 v254, 0x3727c5ac
	v_fmamk_f32 v157, v157, 0x3a000000, v254
	v_mul_f32_e32 v151, 0x4f800000, v157
	s_mov_b32 s9, 0xf800000
	v_cmp_gt_f32_e32 vcc, s9, v157
	s_nop 1
	v_cndmask_b32_e32 v157, v157, v151, vcc
	v_sqrt_f32_e32 v151, v157
	s_nop 0
	v_add_u32_e32 v203, -1, v151
	v_fma_f32 v204, -v203, v151, v157
	v_cmp_ge_f32_e64 s[88:89], 0, v204
	v_add_u32_e32 v204, 1, v151
	s_nop 0
	v_cndmask_b32_e64 v203, v151, v203, s[88:89]
	v_fma_f32 v151, -v204, v151, v157
	v_cmp_lt_f32_e64 s[88:89], 0, v151
	s_nop 1
	v_cndmask_b32_e64 v151, v203, v204, s[88:89]
	v_mul_f32_e32 v203, 0x37800000, v151
	v_cndmask_b32_e32 v151, v151, v203, vcc
	v_mov_b32_e32 v203, 0x260
	v_cmp_class_f32_e32 vcc, v157, v203
	s_nop 1
	v_cndmask_b32_e32 v157, v151, v157, vcc
	v_div_scale_f32 v151, s[88:89], v157, v157, 1.0
	v_rcp_f32_e32 v203, v151
	s_nop 0
	v_fma_f32 v204, -v151, v203, 1.0
	v_fmac_f32_e32 v203, v204, v203
	v_div_scale_f32 v204, vcc, 1.0, v157, 1.0
	v_mul_f32_e32 v205, v204, v203
	v_fma_f32 v254, -v151, v205, v204
	v_fmac_f32_e32 v205, v254, v203
	v_fma_f32 v151, -v151, v205, v204
	v_div_fmas_f32 v151, v151, v203, v205
	v_div_fixup_f32 v155, v151, v157, 1.0
	v_mul_f32_e32 v66, v66, v155
	v_mul_f32_e32 v67, v67, v155
	v_mul_f32_e32 v68, v68, v155
	v_mul_f32_e32 v69, v69, v155
	v_pk_fma_f32 v[66:67], v[2:3], v[66:67], v[10:11]
	v_pk_fma_f32 v[68:69], v[4:5], v[68:69], v[12:13]
	global_store_dwordx4 v129, v[66:69], s[6:7]
	s_waitcnt vmcnt(15)
	v_pk_add_f32 v[158:159], v[158:159], 1.0 op_sel_hi:[1,0]
	v_pk_add_f32 v[160:161], v[160:161], 1.0 op_sel_hi:[1,0]
	v_pk_fma_f32 v[158:159], v[158:159], v[66:67], v[220:221]
	v_pk_fma_f32 v[160:161], v[160:161], v[68:69], v[222:223]
	v_cvt_pk_bf16_f32 v158, v158, v159
	v_cvt_pk_bf16_f32 v159, v160, v161
	global_store_dwordx2 v117, v[158:159], s[10:11]
	v_mul_f32_e32 v70, v70, v155
	v_mul_f32_e32 v71, v71, v155
	v_mul_f32_e32 v72, v72, v155
	v_mul_f32_e32 v73, v73, v155
	v_pk_fma_f32 v[70:71], v[6:7], v[70:71], v[14:15]
	v_pk_fma_f32 v[72:73], v[8:9], v[72:73], v[16:17]
	global_store_dwordx4 v129, v[70:73], s[6:7] offset:1024
	s_waitcnt vmcnt(15)
	v_pk_add_f32 v[162:163], v[162:163], 1.0 op_sel_hi:[1,0]
	v_pk_add_f32 v[164:165], v[164:165], 1.0 op_sel_hi:[1,0]
	v_pk_fma_f32 v[162:163], v[162:163], v[70:71], v[224:225]
	v_pk_fma_f32 v[164:165], v[164:165], v[72:73], v[226:227]
	v_cvt_pk_bf16_f32 v162, v162, v163
	v_cvt_pk_bf16_f32 v163, v164, v165
	global_store_dwordx2 v117, v[162:163], s[10:11] offset:512
	v_mul_f32_e32 v74, v74, v155
	v_mul_f32_e32 v75, v75, v155
	v_mul_f32_e32 v76, v76, v155
	v_mul_f32_e32 v77, v77, v155
	v_pk_fma_f32 v[74:75], v[18:19], v[74:75], v[26:27]
	v_pk_fma_f32 v[76:77], v[20:21], v[76:77], v[28:29]
	global_store_dwordx4 v129, v[74:77], s[6:7] offset:2048
	s_waitcnt vmcnt(15)
	v_pk_add_f32 v[166:167], v[166:167], 1.0 op_sel_hi:[1,0]
	v_pk_add_f32 v[168:169], v[168:169], 1.0 op_sel_hi:[1,0]
	v_pk_fma_f32 v[166:167], v[166:167], v[74:75], v[228:229]
	v_pk_fma_f32 v[168:169], v[168:169], v[76:77], v[230:231]
	v_cvt_pk_bf16_f32 v166, v166, v167
	v_cvt_pk_bf16_f32 v167, v168, v169
	global_store_dwordx2 v117, v[166:167], s[10:11] offset:1024
	v_mul_f32_e32 v78, v78, v155
	v_mul_f32_e32 v79, v79, v155
	v_mul_f32_e32 v80, v80, v155
	v_mul_f32_e32 v81, v81, v155
	v_pk_fma_f32 v[78:79], v[22:23], v[78:79], v[30:31]
	v_pk_fma_f32 v[80:81], v[24:25], v[80:81], v[32:33]
	global_store_dwordx4 v129, v[78:81], s[6:7] offset:3072
	s_waitcnt vmcnt(15)
	v_pk_add_f32 v[176:177], v[176:177], 1.0 op_sel_hi:[1,0]
	v_pk_add_f32 v[178:179], v[178:179], 1.0 op_sel_hi:[1,0]
	v_pk_fma_f32 v[176:177], v[176:177], v[78:79], v[232:233]
	v_pk_fma_f32 v[178:179], v[178:179], v[80:81], v[234:235]
	v_cvt_pk_bf16_f32 v176, v176, v177
	v_cvt_pk_bf16_f32 v177, v178, v179
	global_store_dwordx2 v117, v[176:177], s[10:11] offset:1536
	v_mul_f32_e32 v82, v82, v155
	v_mul_f32_e32 v83, v83, v155
	v_mul_f32_e32 v84, v84, v155
	v_mul_f32_e32 v85, v85, v155
	v_pk_fma_f32 v[82:83], v[34:35], v[82:83], v[42:43]
	v_pk_fma_f32 v[84:85], v[36:37], v[84:85], v[44:45]
	global_store_dwordx4 v131, v[82:85], s[6:7]
	s_waitcnt vmcnt(15)
	v_pk_add_f32 v[180:181], v[180:181], 1.0 op_sel_hi:[1,0]
	v_pk_add_f32 v[182:183], v[182:183], 1.0 op_sel_hi:[1,0]
	v_pk_fma_f32 v[180:181], v[180:181], v[82:83], v[236:237]
	v_pk_fma_f32 v[182:183], v[182:183], v[84:85], v[238:239]
	v_cvt_pk_bf16_f32 v180, v180, v181
	v_cvt_pk_bf16_f32 v181, v182, v183
	global_store_dwordx2 v117, v[180:181], s[10:11] offset:2048
	v_mul_f32_e32 v86, v86, v155
	v_mul_f32_e32 v87, v87, v155
	v_mul_f32_e32 v88, v88, v155
	v_mul_f32_e32 v89, v89, v155
	v_pk_fma_f32 v[86:87], v[38:39], v[86:87], v[46:47]
	v_pk_fma_f32 v[88:89], v[40:41], v[88:89], v[48:49]
	global_store_dwordx4 v131, v[86:89], s[6:7] offset:1024
	s_waitcnt vmcnt(15)
	v_pk_add_f32 v[184:185], v[184:185], 1.0 op_sel_hi:[1,0]
	v_pk_add_f32 v[186:187], v[186:187], 1.0 op_sel_hi:[1,0]
	v_pk_fma_f32 v[184:185], v[184:185], v[86:87], v[240:241]
	v_pk_fma_f32 v[186:187], v[186:187], v[88:89], v[242:243]
	v_cvt_pk_bf16_f32 v184, v184, v185
	v_cvt_pk_bf16_f32 v185, v186, v187
	global_store_dwordx2 v117, v[184:185], s[10:11] offset:2560
	v_mul_f32_e32 v90, v90, v155
	v_mul_f32_e32 v91, v91, v155
	v_mul_f32_e32 v92, v92, v155
	v_mul_f32_e32 v93, v93, v155
	v_pk_fma_f32 v[90:91], v[50:51], v[90:91], v[58:59]
	v_pk_fma_f32 v[92:93], v[52:53], v[92:93], v[60:61]
	global_store_dwordx4 v131, v[90:93], s[6:7] offset:2048
	s_waitcnt vmcnt(15)
	v_pk_add_f32 v[212:213], v[212:213], 1.0 op_sel_hi:[1,0]
	v_pk_add_f32 v[214:215], v[214:215], 1.0 op_sel_hi:[1,0]
	v_pk_fma_f32 v[212:213], v[212:213], v[90:91], v[244:245]
	v_pk_fma_f32 v[214:215], v[214:215], v[92:93], v[246:247]
	v_cvt_pk_bf16_f32 v212, v212, v213
	v_cvt_pk_bf16_f32 v213, v214, v215
	global_store_dwordx2 v117, v[212:213], s[10:11] offset:3072
	v_mul_f32_e32 v94, v94, v155
	v_mul_f32_e32 v95, v95, v155
	v_mul_f32_e32 v96, v96, v155
	v_mul_f32_e32 v97, v97, v155
	v_pk_fma_f32 v[94:95], v[54:55], v[94:95], v[62:63]
	v_pk_fma_f32 v[96:97], v[56:57], v[96:97], v[64:65]
	global_store_dwordx4 v131, v[94:97], s[6:7] offset:3072
	s_waitcnt vmcnt(15)
	v_pk_add_f32 v[216:217], v[216:217], 1.0 op_sel_hi:[1,0]
	v_pk_add_f32 v[218:219], v[218:219], 1.0 op_sel_hi:[1,0]
	v_pk_fma_f32 v[216:217], v[216:217], v[94:95], v[248:249]
	v_pk_fma_f32 v[218:219], v[218:219], v[96:97], v[250:251]
	v_cvt_pk_bf16_f32 v216, v216, v217
	v_cvt_pk_bf16_f32 v217, v218, v219
	global_store_dwordx2 v117, v[216:217], s[10:11] offset:3584
	s_branch .Lp6_r3_done
.Lp6_r3_sample:
	s_waitcnt vmcnt(0)
	s_lshl_b32 s1, s0, 13
	s_add_u32 s6, s40, s1
	s_addc_u32 s7, s41, 0
	s_lshl_b32 s1, s0, 12
	s_add_u32 s10, s44, s1
	s_addc_u32 s11, s45, 0
	s_add_i32 s1, s0, 0xffffe000
	s_lshl_b32 s9, s1, 13
	s_add_u32 s32, s42, s9
	s_addc_u32 s33, s43, 0
	s_add_u32 s50, s32, 0x100000
	s_addc_u32 s51, s33, 0
	s_add_u32 s52, s50, 0x100000
	s_addc_u32 s53, s51, 0
	s_add_u32 s54, s52, 0x100000
	s_addc_u32 s55, s53, 0
	s_add_u32 s56, s54, 0x100000
	s_addc_u32 s57, s55, 0
	s_add_u32 s60, s56, 0x100000
	s_addc_u32 s61, s57, 0
	s_add_u32 s62, s60, 0x100000
	s_addc_u32 s63, s61, 0
	s_add_u32 s74, s62, 0x100000
	s_addc_u32 s75, s63, 0
	v_readfirstlane_b32 s86, v114
	v_readfirstlane_b32 s87, v115
	s_add_u32 s86, s86, s9
	s_addc_u32 s87, s87, 0
	s_add_i32 s1, s1, 4
	s_lshl_b32 s1, s1, 16
	s_add_u32 s16, s14, s1
	s_addc_u32 s17, s15, 0
	global_load_dwordx4 v[158:161], v129, s[32:33]
	global_load_dwordx4 v[162:165], v129, s[50:51]
	global_load_dwordx4 v[166:169], v129, s[52:53]
	global_load_dwordx4 v[176:179], v129, s[54:55]
	global_load_dwordx4 v[180:183], v129, s[56:57]
	global_load_dwordx4 v[184:187], v129, s[60:61]
	global_load_dwordx4 v[212:215], v129, s[62:63]
	global_load_dwordx4 v[216:219], v129, s[74:75]
	v_lshlrev_b32_e32 v151, 2, v98
	global_load_dwordx4 v[220:223], v151, s[16:17]
	global_load_dwordx4 v[224:227], v129, s[86:87]
	global_load_dwordx4 v[228:231], v129, s[32:33] offset:1024
	global_load_dwordx4 v[232:235], v129, s[50:51] offset:1024
	global_load_dwordx4 v[236:239], v129, s[52:53] offset:1024
	global_load_dwordx4 v[240:243], v129, s[54:55] offset:1024
	global_load_dwordx4 v[244:247], v129, s[56:57] offset:1024
	global_load_dwordx4 v[248:251], v129, s[60:61] offset:1024
	s_waitcnt vmcnt(15)
	v_pk_add_f32 v[252:253], v[158:159], 0 op_sel_hi:[1,0]
	v_pk_add_f32 v[148:149], v[160:161], 0 op_sel_hi:[1,0]
	global_load_dwordx4 v[158:161], v129, s[62:63] offset:1024
	s_waitcnt vmcnt(15)
	v_pk_add_f32 v[252:253], v[252:253], v[162:163]
	v_pk_add_f32 v[148:149], v[148:149], v[164:165]
	global_load_dwordx4 v[162:165], v129, s[74:75] offset:1024
	s_waitcnt vmcnt(15)
	v_pk_add_f32 v[252:253], v[252:253], v[166:167]
	v_pk_add_f32 v[148:149], v[148:149], v[168:169]
	v_lshlrev_b32_e32 v151, 2, v100
	global_load_dwordx4 v[166:169], v151, s[16:17]
	s_waitcnt vmcnt(15)
	v_pk_add_f32 v[252:253], v[252:253], v[176:177]
	v_pk_add_f32 v[148:149], v[148:149], v[178:179]
	global_load_dwordx4 v[176:179], v129, s[86:87] offset:1024
	s_waitcnt vmcnt(15)
	v_pk_add_f32 v[252:253], v[252:253], v[180:181]
	v_pk_add_f32 v[148:149], v[148:149], v[182:183]
	global_load_dwordx4 v[180:183], v129, s[32:33] offset:2048
	s_waitcnt vmcnt(15)
	v_pk_add_f32 v[252:253], v[252:253], v[184:185]
	v_pk_add_f32 v[148:149], v[148:149], v[186:187]
	global_load_dwordx4 v[184:187], v129, s[50:51] offset:2048
	s_waitcnt vmcnt(15)
	v_pk_add_f32 v[252:253], v[252:253], v[212:213]
	v_pk_add_f32 v[148:149], v[148:149], v[214:215]
	global_load_dwordx4 v[212:215], v129, s[52:53] offset:2048
	s_waitcnt vmcnt(15)
	v_pk_add_f32 v[252:253], v[252:253], v[216:217]
	v_pk_add_f32 v[148:149], v[148:149], v[218:219]
	global_load_dwordx4 v[216:219], v129, s[54:55] offset:2048
	s_waitcnt vmcnt(15)
	v_pk_mul_f32 v[252:253], v[252:253], v[220:221]
	v_pk_mul_f32 v[148:149], v[148:149], v[222:223]
	global_load_dwordx4 v[220:223], v129, s[56:57] offset:2048
	s_waitcnt vmcnt(15)
	v_fma_f32 v66, v224, s3, v252
	v_fma_f32 v67, v225, s3, v253
	v_fma_f32 v68, v226, s3, v148
	v_fma_f32 v69, v227, s3, v149
	global_load_dwordx4 v[224:227], v129, s[60:61] offset:2048
	s_waitcnt vmcnt(15)
	v_pk_add_f32 v[252:253], v[228:229], 0 op_sel_hi:[1,0]
	v_pk_add_f32 v[148:149], v[230:231], 0 op_sel_hi:[1,0]
	global_load_dwordx4 v[228:231], v129, s[62:63] offset:2048
	s_waitcnt vmcnt(15)
	v_pk_add_f32 v[252:253], v[252:253], v[232:233]
	v_pk_add_f32 v[148:149], v[148:149], v[234:235]
	global_load_dwordx4 v[232:235], v129, s[74:75] offset:2048
	s_waitcnt vmcnt(15)
	v_pk_add_f32 v[252:253], v[252:253], v[236:237]
	v_pk_add_f32 v[148:149], v[148:149], v[238:239]
	v_lshlrev_b32_e32 v151, 2, v102
	global_load_dwordx4 v[236:239], v151, s[16:17]
	s_waitcnt vmcnt(15)
	v_pk_add_f32 v[252:253], v[252:253], v[240:241]
	v_pk_add_f32 v[148:149], v[148:149], v[242:243]
	global_load_dwordx4 v[240:243], v129, s[86:87] offset:2048
	s_waitcnt vmcnt(15)
	v_pk_add_f32 v[252:253], v[252:253], v[244:245]
	v_pk_add_f32 v[148:149], v[148:149], v[246:247]
	global_load_dwordx4 v[244:247], v129, s[32:33] offset:3072
	s_waitcnt vmcnt(15)
	v_pk_add_f32 v[252:253], v[252:253], v[248:249]
	v_pk_add_f32 v[148:149], v[148:149], v[250:251]
	global_load_dwordx4 v[248:251], v129, s[50:51] offset:3072
	s_waitcnt vmcnt(15)
	v_pk_add_f32 v[252:253], v[252:253], v[158:159]
	v_pk_add_f32 v[148:149], v[148:149], v[160:161]
	global_load_dwordx4 v[158:161], v129, s[52:53] offset:3072
	s_waitcnt vmcnt(15)
	v_pk_add_f32 v[252:253], v[252:253], v[162:163]
	v_pk_add_f32 v[148:149], v[148:149], v[164:165]
	global_load_dwordx4 v[162:165], v129, s[54:55] offset:3072
	s_waitcnt vmcnt(15)
	v_pk_mul_f32 v[252:253], v[252:253], v[166:167]
	v_pk_mul_f32 v[148:149], v[148:149], v[168:169]
	global_load_dwordx4 v[166:169], v129, s[56:57] offset:3072
	s_waitcnt vmcnt(15)
	v_fma_f32 v70, v176, s3, v252
	v_fma_f32 v71, v177, s3, v253
	v_fma_f32 v72, v178, s3, v148
	v_fma_f32 v73, v179, s3, v149
	global_load_dwordx4 v[176:179], v129, s[60:61] offset:3072
	s_waitcnt vmcnt(15)
	v_pk_add_f32 v[252:253], v[180:181], 0 op_sel_hi:[1,0]
	v_pk_add_f32 v[148:149], v[182:183], 0 op_sel_hi:[1,0]
	global_load_dwordx4 v[180:183], v129, s[62:63] offset:3072
	s_waitcnt vmcnt(15)
	v_pk_add_f32 v[252:253], v[252:253], v[184:185]
	v_pk_add_f32 v[148:149], v[148:149], v[186:187]
	global_load_dwordx4 v[184:187], v129, s[74:75] offset:3072
	s_waitcnt vmcnt(15)
	v_pk_add_f32 v[252:253], v[252:253], v[212:213]
	v_pk_add_f32 v[148:149], v[148:149], v[214:215]
	v_lshlrev_b32_e32 v151, 2, v104
	global_load_dwordx4 v[212:215], v151, s[16:17]
	s_waitcnt vmcnt(15)
	v_pk_add_f32 v[252:253], v[252:253], v[216:217]
	v_pk_add_f32 v[148:149], v[148:149], v[218:219]
	global_load_dwordx4 v[216:219], v129, s[86:87] offset:3072
	s_waitcnt vmcnt(15)
	v_pk_add_f32 v[252:253], v[252:253], v[220:221]
	v_pk_add_f32 v[148:149], v[148:149], v[222:223]
	global_load_dwordx4 v[220:223], v131, s[32:33]
	s_waitcnt vmcnt(15)
	v_pk_add_f32 v[252:253], v[252:253], v[224:225]
	v_pk_add_f32 v[148:149], v[148:149], v[226:227]
	global_load_dwordx4 v[224:227], v131, s[50:51]
	s_waitcnt vmcnt(15)
	v_pk_add_f32 v[252:253], v[252:253], v[228:229]
	v_pk_add_f32 v[148:149], v[148:149], v[230:231]
	global_load_dwordx4 v[228:231], v131, s[52:53]
	s_waitcnt vmcnt(15)
	v_pk_add_f32 v[252:253], v[252:253], v[232:233]
	v_pk_add_f32 v[148:149], v[148:149], v[234:235]
	global_load_dwordx4 v[232:235], v131, s[54:55]
	s_waitcnt vmcnt(15)
	v_pk_mul_f32 v[252:253], v[252:253], v[236:237]
	v_pk_mul_f32 v[148:149], v[148:149], v[238:239]
	global_load_dwordx4 v[236:239], v131, s[56:57]
	s_waitcnt vmcnt(15)
	v_fma_f32 v74, v240, s3, v252
	v_fma_f32 v75, v241, s3, v253
	v_fma_f32 v76, v242, s3, v148
	v_fma_f32 v77, v243, s3, v149
	global_load_dwordx4 v[240:243], v131, s[60:61]
	s_waitcnt vmcnt(15)
	v_pk_add_f32 v[252:253], v[244:245], 0 op_sel_hi:[1,0]
	v_pk_add_f32 v[148:149], v[246:247], 0 op_sel_hi:[1,0]
	global_load_dwordx4 v[244:247], v131, s[62:63]
	s_waitcnt vmcnt(15)
	v_pk_add_f32 v[252:253], v[252:253], v[248:249]
	v_pk_add_f32 v[148:149], v[148:149], v[250:251]
	global_load_dwordx4 v[248:251], v131, s[74:75]
	s_waitcnt vmcnt(15)
	v_pk_add_f32 v[252:253], v[252:253], v[158:159]
	v_pk_add_f32 v[148:149], v[148:149], v[160:161]
	v_lshlrev_b32_e32 v151, 2, v106
	global_load_dwordx4 v[158:161], v151, s[16:17]
	s_waitcnt vmcnt(15)
	v_pk_add_f32 v[252:253], v[252:253], v[162:163]
	v_pk_add_f32 v[148:149], v[148:149], v[164:165]
	global_load_dwordx4 v[162:165], v131, s[86:87]
	s_waitcnt vmcnt(15)
	v_pk_add_f32 v[252:253], v[252:253], v[166:167]
	v_pk_add_f32 v[148:149], v[148:149], v[168:169]
	global_load_dwordx4 v[166:169], v131, s[32:33] offset:1024
	s_waitcnt vmcnt(15)
	v_pk_add_f32 v[252:253], v[252:253], v[176:177]
	v_pk_add_f32 v[148:149], v[148:149], v[178:179]
	global_load_dwordx4 v[176:179], v131, s[50:51] offset:1024
	s_waitcnt vmcnt(15)
	v_pk_add_f32 v[252:253], v[252:253], v[180:181]
	v_pk_add_f32 v[148:149], v[148:149], v[182:183]
	global_load_dwordx4 v[180:183], v131, s[52:53] offset:1024
	s_waitcnt vmcnt(15)
	v_pk_add_f32 v[252:253], v[252:253], v[184:185]
	v_pk_add_f32 v[148:149], v[148:149], v[186:187]
	global_load_dwordx4 v[184:187], v131, s[54:55] offset:1024
	s_waitcnt vmcnt(15)
	v_pk_mul_f32 v[252:253], v[252:253], v[212:213]
	v_pk_mul_f32 v[148:149], v[148:149], v[214:215]
	global_load_dwordx4 v[212:215], v131, s[56:57] offset:1024
	s_waitcnt vmcnt(15)
	v_fma_f32 v78, v216, s3, v252
	v_fma_f32 v79, v217, s3, v253
	v_fma_f32 v80, v218, s3, v148
	v_fma_f32 v81, v219, s3, v149
	global_load_dwordx4 v[216:219], v131, s[60:61] offset:1024
	s_waitcnt vmcnt(15)
	v_pk_add_f32 v[252:253], v[220:221], 0 op_sel_hi:[1,0]
	v_pk_add_f32 v[148:149], v[222:223], 0 op_sel_hi:[1,0]
	global_load_dwordx4 v[220:223], v131, s[62:63] offset:1024
	s_waitcnt vmcnt(15)
	v_pk_add_f32 v[252:253], v[252:253], v[224:225]
	v_pk_add_f32 v[148:149], v[148:149], v[226:227]
	global_load_dwordx4 v[224:227], v131, s[74:75] offset:1024
	s_waitcnt vmcnt(15)
	v_pk_add_f32 v[252:253], v[252:253], v[228:229]
	v_pk_add_f32 v[148:149], v[148:149], v[230:231]
	v_lshlrev_b32_e32 v151, 2, v108
	global_load_dwordx4 v[228:231], v151, s[16:17]
	s_waitcnt vmcnt(15)
	v_pk_add_f32 v[252:253], v[252:253], v[232:233]
	v_pk_add_f32 v[148:149], v[148:149], v[234:235]
	global_load_dwordx4 v[232:235], v131, s[86:87] offset:1024
	s_waitcnt vmcnt(15)
	v_pk_add_f32 v[252:253], v[252:253], v[236:237]
	v_pk_add_f32 v[148:149], v[148:149], v[238:239]
	global_load_dwordx4 v[236:239], v131, s[32:33] offset:2048
	s_waitcnt vmcnt(15)
	v_pk_add_f32 v[252:253], v[252:253], v[240:241]
	v_pk_add_f32 v[148:149], v[148:149], v[242:243]
	global_load_dwordx4 v[240:243], v131, s[50:51] offset:2048
	s_waitcnt vmcnt(15)
	v_pk_add_f32 v[252:253], v[252:253], v[244:245]
	v_pk_add_f32 v[148:149], v[148:149], v[246:247]
	global_load_dwordx4 v[244:247], v131, s[52:53] offset:2048
	s_waitcnt vmcnt(15)
	v_pk_add_f32 v[252:253], v[252:253], v[248:249]
	v_pk_add_f32 v[148:149], v[148:149], v[250:251]
	global_load_dwordx4 v[248:251], v131, s[54:55] offset:2048
	s_waitcnt vmcnt(15)
	v_pk_mul_f32 v[252:253], v[252:253], v[158:159]
	v_pk_mul_f32 v[148:149], v[148:149], v[160:161]
	global_load_dwordx4 v[158:161], v131, s[56:57] offset:2048
	s_waitcnt vmcnt(15)
	v_fma_f32 v82, v162, s3, v252
	v_fma_f32 v83, v163, s3, v253
	v_fma_f32 v84, v164, s3, v148
	v_fma_f32 v85, v165, s3, v149
	global_load_dwordx4 v[162:165], v131, s[60:61] offset:2048
	s_waitcnt vmcnt(15)
	v_pk_add_f32 v[252:253], v[166:167], 0 op_sel_hi:[1,0]
	v_pk_add_f32 v[148:149], v[168:169], 0 op_sel_hi:[1,0]
	global_load_dwordx4 v[166:169], v131, s[62:63] offset:2048
	s_waitcnt vmcnt(15)
	v_pk_add_f32 v[252:253], v[252:253], v[176:177]
	v_pk_add_f32 v[148:149], v[148:149], v[178:179]
	global_load_dwordx4 v[176:179], v131, s[74:75] offset:2048
	s_waitcnt vmcnt(15)
	v_pk_add_f32 v[252:253], v[252:253], v[180:181]
	v_pk_add_f32 v[148:149], v[148:149], v[182:183]
	v_lshlrev_b32_e32 v151, 2, v110
	global_load_dwordx4 v[180:183], v151, s[16:17]
	s_waitcnt vmcnt(15)
	v_pk_add_f32 v[252:253], v[252:253], v[184:185]
	v_pk_add_f32 v[148:149], v[148:149], v[186:187]
	global_load_dwordx4 v[184:187], v131, s[86:87] offset:2048
	s_waitcnt vmcnt(15)
	v_pk_add_f32 v[252:253], v[252:253], v[212:213]
	v_pk_add_f32 v[148:149], v[148:149], v[214:215]
	global_load_dwordx4 v[212:215], v131, s[32:33] offset:3072
	s_waitcnt vmcnt(15)
	v_pk_add_f32 v[252:253], v[252:253], v[216:217]
	v_pk_add_f32 v[148:149], v[148:149], v[218:219]
	global_load_dwordx4 v[216:219], v131, s[50:51] offset:3072
	s_waitcnt vmcnt(15)
	v_pk_add_f32 v[252:253], v[252:253], v[220:221]
	v_pk_add_f32 v[148:149], v[148:149], v[222:223]
	global_load_dwordx4 v[220:223], v131, s[52:53] offset:3072
	s_waitcnt vmcnt(15)
	v_pk_add_f32 v[252:253], v[252:253], v[224:225]
	v_pk_add_f32 v[148:149], v[148:149], v[226:227]
	global_load_dwordx4 v[224:227], v131, s[54:55] offset:3072
	s_waitcnt vmcnt(15)
	v_pk_mul_f32 v[252:253], v[252:253], v[228:229]
	v_pk_mul_f32 v[148:149], v[148:149], v[230:231]
	global_load_dwordx4 v[228:231], v131, s[56:57] offset:3072
	s_waitcnt vmcnt(15)
	v_fma_f32 v86, v232, s3, v252
	v_fma_f32 v87, v233, s3, v253
	v_fma_f32 v88, v234, s3, v148
	v_fma_f32 v89, v235, s3, v149
	global_load_dwordx4 v[232:235], v131, s[60:61] offset:3072
	s_waitcnt vmcnt(15)
	v_pk_add_f32 v[252:253], v[236:237], 0 op_sel_hi:[1,0]
	v_pk_add_f32 v[148:149], v[238:239], 0 op_sel_hi:[1,0]
	global_load_dwordx4 v[236:239], v131, s[62:63] offset:3072
	s_waitcnt vmcnt(15)
	v_pk_add_f32 v[252:253], v[252:253], v[240:241]
	v_pk_add_f32 v[148:149], v[148:149], v[242:243]
	global_load_dwordx4 v[240:243], v131, s[74:75] offset:3072
	s_waitcnt vmcnt(15)
	v_pk_add_f32 v[252:253], v[252:253], v[244:245]
	v_pk_add_f32 v[148:149], v[148:149], v[246:247]
	v_lshlrev_b32_e32 v151, 2, v112
	global_load_dwordx4 v[244:247], v151, s[16:17]
	s_waitcnt vmcnt(15)
	v_pk_add_f32 v[252:253], v[252:253], v[248:249]
	v_pk_add_f32 v[148:149], v[148:149], v[250:251]
	global_load_dwordx4 v[248:251], v131, s[86:87] offset:3072
	s_waitcnt vmcnt(15)
	v_pk_add_f32 v[252:253], v[252:253], v[158:159]
	v_pk_add_f32 v[148:149], v[148:149], v[160:161]
	s_waitcnt vmcnt(14)
	v_pk_add_f32 v[252:253], v[252:253], v[162:163]
	v_pk_add_f32 v[148:149], v[148:149], v[164:165]
	s_waitcnt vmcnt(13)
	v_pk_add_f32 v[252:253], v[252:253], v[166:167]
	v_pk_add_f32 v[148:149], v[148:149], v[168:169]
	s_waitcnt vmcnt(12)
	v_pk_add_f32 v[252:253], v[252:253], v[176:177]
	v_pk_add_f32 v[148:149], v[148:149], v[178:179]
	s_waitcnt vmcnt(11)
	v_pk_mul_f32 v[252:253], v[252:253], v[180:181]
	v_pk_mul_f32 v[148:149], v[148:149], v[182:183]
	s_waitcnt vmcnt(10)
	v_fma_f32 v90, v184, s3, v252
	v_fma_f32 v91, v185, s3, v253
	v_fma_f32 v92, v186, s3, v148
	v_fma_f32 v93, v187, s3, v149
	s_waitcnt vmcnt(9)
	v_pk_add_f32 v[252:253], v[212:213], 0 op_sel_hi:[1,0]
	v_pk_add_f32 v[148:149], v[214:215], 0 op_sel_hi:[1,0]
	s_waitcnt vmcnt(8)
	v_pk_add_f32 v[252:253], v[252:253], v[216:217]
	v_pk_add_f32 v[148:149], v[148:149], v[218:219]
	s_waitcnt vmcnt(7)
	v_pk_add_f32 v[252:253], v[252:253], v[220:221]
	v_pk_add_f32 v[148:149], v[148:149], v[222:223]
	s_waitcnt vmcnt(6)
	v_pk_add_f32 v[252:253], v[252:253], v[224:225]
	v_pk_add_f32 v[148:149], v[148:149], v[226:227]
	s_waitcnt vmcnt(5)
	v_pk_add_f32 v[252:253], v[252:253], v[228:229]
	v_pk_add_f32 v[148:149], v[148:149], v[230:231]
	s_waitcnt vmcnt(4)
	v_pk_add_f32 v[252:253], v[252:253], v[232:233]
	v_pk_add_f32 v[148:149], v[148:149], v[234:235]
	s_waitcnt vmcnt(3)
	v_pk_add_f32 v[252:253], v[252:253], v[236:237]
	v_pk_add_f32 v[148:149], v[148:149], v[238:239]
	s_waitcnt vmcnt(2)
	v_pk_add_f32 v[252:253], v[252:253], v[240:241]
	v_pk_add_f32 v[148:149], v[148:149], v[242:243]
	s_waitcnt vmcnt(1)
	v_pk_mul_f32 v[252:253], v[252:253], v[244:245]
	v_pk_mul_f32 v[148:149], v[148:149], v[246:247]
	s_waitcnt vmcnt(0)
	v_fma_f32 v94, v248, s3, v252
	v_fma_f32 v95, v249, s3, v253
	v_fma_f32 v96, v250, s3, v148
	v_fma_f32 v97, v251, s3, v149
	v_lshlrev_b32_e32 v151, 2, v116
	global_load_dwordx4 v[158:161], v151, s[16:17]
	v_lshlrev_b32_e32 v151, 2, v118
	global_load_dwordx4 v[220:223], v151, s[16:17]
	v_lshlrev_b32_e32 v151, 2, v120
	global_load_dwordx4 v[162:165], v151, s[16:17]
	v_lshlrev_b32_e32 v151, 2, v122
	global_load_dwordx4 v[224:227], v151, s[16:17]
	v_lshlrev_b32_e32 v151, 2, v124
	global_load_dwordx4 v[166:169], v151, s[16:17]
	v_lshlrev_b32_e32 v151, 2, v126
	global_load_dwordx4 v[228:231], v151, s[16:17]
	v_lshlrev_b32_e32 v151, 2, v128
	global_load_dwordx4 v[176:179], v151, s[16:17]
	v_lshlrev_b32_e32 v151, 2, v130
	global_load_dwordx4 v[232:235], v151, s[16:17]
	v_lshlrev_b32_e32 v151, 2, v132
	global_load_dwordx4 v[180:183], v151, s[16:17]
	v_lshlrev_b32_e32 v151, 2, v134
	global_load_dwordx4 v[236:239], v151, s[16:17]
	v_lshlrev_b32_e32 v151, 2, v136
	global_load_dwordx4 v[184:187], v151, s[16:17]
	v_lshlrev_b32_e32 v151, 2, v138
	global_load_dwordx4 v[240:243], v151, s[16:17]
	v_lshlrev_b32_e32 v151, 2, v140
	global_load_dwordx4 v[212:215], v151, s[16:17]
	v_lshlrev_b32_e32 v151, 2, v142
	global_load_dwordx4 v[244:247], v151, s[16:17]
	v_lshlrev_b32_e32 v151, 2, v144
	global_load_dwordx4 v[216:219], v151, s[16:17]
	v_lshlrev_b32_e32 v151, 2, v146
	global_load_dwordx4 v[248:251], v151, s[16:17]
	v_add_f32_e32 v151, v66, v67
	v_add_f32_e32 v155, v68, v69
	v_add_f32_e32 v151, v151, v155
	v_add_f32_e32 v153, 0, v151
	v_add_f32_e32 v151, v70, v71
	v_add_f32_e32 v155, v72, v73
	v_add_f32_e32 v151, v151, v155
	v_add_f32_e32 v153, v153, v151
	v_add_f32_e32 v151, v74, v75
	v_add_f32_e32 v155, v76, v77
	v_add_f32_e32 v151, v151, v155
	v_add_f32_e32 v153, v153, v151
	v_add_f32_e32 v151, v78, v79
	v_add_f32_e32 v155, v80, v81
	v_add_f32_e32 v151, v151, v155
	v_add_f32_e32 v153, v153, v151
	v_add_f32_e32 v151, v82, v83
	v_add_f32_e32 v155, v84, v85
	v_add_f32_e32 v151, v151, v155
	v_add_f32_e32 v153, v153, v151
	v_add_f32_e32 v151, v86, v87
	v_add_f32_e32 v155, v88, v89
	v_add_f32_e32 v151, v151, v155
	v_add_f32_e32 v153, v153, v151
	v_add_f32_e32 v151, v90, v91
	v_add_f32_e32 v155, v92, v93
	v_add_f32_e32 v151, v151, v155
	v_add_f32_e32 v153, v153, v151
	v_add_f32_e32 v151, v94, v95
	v_add_f32_e32 v155, v96, v97
	v_add_f32_e32 v151, v151, v155
	v_add_f32_e32 v153, v153, v151
	ds_bpermute_b32 v151, v99, v153
	s_waitcnt lgkmcnt(0)
	v_add_f32_e32 v153, v153, v151
	ds_bpermute_b32 v151, v101, v153
	s_waitcnt lgkmcnt(0)
	v_add_f32_e32 v153, v153, v151
	ds_bpermute_b32 v151, v103, v153
	s_waitcnt lgkmcnt(0)
	v_add_f32_e32 v153, v153, v151
	ds_bpermute_b32 v151, v105, v153
	s_waitcnt lgkmcnt(0)
	v_add_f32_e32 v153, v153, v151
	ds_bpermute_b32 v151, v107, v153
	s_waitcnt lgkmcnt(0)
	v_add_f32_e32 v153, v153, v151
	ds_bpermute_b32 v151, v119, v153
	s_waitcnt lgkmcnt(0)
	v_add_f32_e32 v153, v153, v151
	v_fmac_f32_e32 v66, 0xba000000, v153
	v_fmac_f32_e32 v67, 0xba000000, v153
	v_fmac_f32_e32 v68, 0xba000000, v153
	v_fmac_f32_e32 v69, 0xba000000, v153
	v_fmac_f32_e32 v70, 0xba000000, v153
	v_fmac_f32_e32 v71, 0xba000000, v153
	v_fmac_f32_e32 v72, 0xba000000, v153
	v_fmac_f32_e32 v73, 0xba000000, v153
	v_fmac_f32_e32 v74, 0xba000000, v153
	v_fmac_f32_e32 v75, 0xba000000, v153
	v_fmac_f32_e32 v76, 0xba000000, v153
	v_fmac_f32_e32 v77, 0xba000000, v153
	v_fmac_f32_e32 v78, 0xba000000, v153
	v_fmac_f32_e32 v79, 0xba000000, v153
	v_fmac_f32_e32 v80, 0xba000000, v153
	v_fmac_f32_e32 v81, 0xba000000, v153
	v_fmac_f32_e32 v82, 0xba000000, v153
	v_fmac_f32_e32 v83, 0xba000000, v153
	v_fmac_f32_e32 v84, 0xba000000, v153
	v_fmac_f32_e32 v85, 0xba000000, v153
	v_fmac_f32_e32 v86, 0xba000000, v153
	v_fmac_f32_e32 v87, 0xba000000, v153
	v_fmac_f32_e32 v88, 0xba000000, v153
	v_fmac_f32_e32 v89, 0xba000000, v153
	v_fmac_f32_e32 v90, 0xba000000, v153
	v_fmac_f32_e32 v91, 0xba000000, v153
	v_fmac_f32_e32 v92, 0xba000000, v153
	v_fmac_f32_e32 v93, 0xba000000, v153
	v_fmac_f32_e32 v94, 0xba000000, v153
	v_fmac_f32_e32 v95, 0xba000000, v153
	v_fmac_f32_e32 v96, 0xba000000, v153
	v_fmac_f32_e32 v97, 0xba000000, v153
	v_mul_f32_e32 v151, v67, v67
	v_fma_f32 v151, v66, v66, v151
	v_mul_f32_e32 v155, v69, v69
	v_fma_f32 v155, v68, v68, v155
	v_add_f32_e32 v151, v151, v155
	v_add_f32_e32 v157, 0, v151
	v_mul_f32_e32 v151, v71, v71
	v_fma_f32 v151, v70, v70, v151
	v_mul_f32_e32 v155, v73, v73
	v_fma_f32 v155, v72, v72, v155
	v_add_f32_e32 v151, v151, v155
	v_add_f32_e32 v157, v157, v151
	v_mul_f32_e32 v151, v75, v75
	v_fma_f32 v151, v74, v74, v151
	v_mul_f32_e32 v155, v77, v77
	v_fma_f32 v155, v76, v76, v155
	v_add_f32_e32 v151, v151, v155
	v_add_f32_e32 v157, v157, v151
	v_mul_f32_e32 v151, v79, v79
	v_fma_f32 v151, v78, v78, v151
	v_mul_f32_e32 v155, v81, v81
	v_fma_f32 v155, v80, v80, v155
	v_add_f32_e32 v151, v151, v155
	v_add_f32_e32 v157, v157, v151
	v_mul_f32_e32 v151, v83, v83
	v_fma_f32 v151, v82, v82, v151
	v_mul_f32_e32 v155, v85, v85
	v_fma_f32 v155, v84, v84, v155
	v_add_f32_e32 v151, v151, v155
	v_add_f32_e32 v157, v157, v151
	v_mul_f32_e32 v151, v87, v87
	v_fma_f32 v151, v86, v86, v151
	v_mul_f32_e32 v155, v89, v89
	v_fma_f32 v155, v88, v88, v155
	v_add_f32_e32 v151, v151, v155
	v_add_f32_e32 v157, v157, v151
	v_mul_f32_e32 v151, v91, v91
	v_fma_f32 v151, v90, v90, v151
	v_mul_f32_e32 v155, v93, v93
	v_fma_f32 v155, v92, v92, v155
	v_add_f32_e32 v151, v151, v155
	v_add_f32_e32 v157, v157, v151
	v_mul_f32_e32 v151, v95, v95
	v_fma_f32 v151, v94, v94, v151
	v_mul_f32_e32 v155, v97, v97
	v_fma_f32 v155, v96, v96, v155
	v_add_f32_e32 v151, v151, v155
	v_add_f32_e32 v157, v157, v151
	ds_bpermute_b32 v151, v99, v157
	s_waitcnt lgkmcnt(0)
	v_add_f32_e32 v157, v157, v151
	ds_bpermute_b32 v151, v101, v157
	s_waitcnt lgkmcnt(0)
	v_add_f32_e32 v157, v157, v151
	ds_bpermute_b32 v151, v103, v157
	s_waitcnt lgkmcnt(0)
	v_add_f32_e32 v157, v157, v151
	ds_bpermute_b32 v151, v105, v157
	s_waitcnt lgkmcnt(0)
	v_add_f32_e32 v157, v157, v151
	ds_bpermute_b32 v151, v107, v157
	s_waitcnt lgkmcnt(0)
	v_add_f32_e32 v157, v157, v151
	ds_bpermute_b32 v151, v119, v157
	s_waitcnt lgkmcnt(0)
	v_add_f32_e32 v157, v157, v151
	v_mov_b32_e32 v254, 0x3727c5ac
	v_fmamk_f32 v157, v157, 0x3a000000, v254
	v_mul_f32_e32 v151, 0x4f800000, v157
	s_mov_b32 s9, 0xf800000
	v_cmp_gt_f32_e32 vcc, s9, v157
	s_nop 1
	v_cndmask_b32_e32 v157, v157, v151, vcc
	v_sqrt_f32_e32 v151, v157
	s_nop 0
	v_add_u32_e32 v203, -1, v151
	v_fma_f32 v204, -v203, v151, v157
	v_cmp_ge_f32_e64 s[88:89], 0, v204
	v_add_u32_e32 v204, 1, v151
	s_nop 0
	v_cndmask_b32_e64 v203, v151, v203, s[88:89]
	v_fma_f32 v151, -v204, v151, v157
	v_cmp_lt_f32_e64 s[88:89], 0, v151
	s_nop 1
	v_cndmask_b32_e64 v151, v203, v204, s[88:89]
	v_mul_f32_e32 v203, 0x37800000, v151
	v_cndmask_b32_e32 v151, v151, v203, vcc
	v_mov_b32_e32 v203, 0x260
	v_cmp_class_f32_e32 vcc, v157, v203
	s_nop 1
	v_cndmask_b32_e32 v157, v151, v157, vcc
	v_div_scale_f32 v151, s[88:89], v157, v157, 1.0
	v_rcp_f32_e32 v203, v151
	s_nop 0
	v_fma_f32 v204, -v151, v203, 1.0
	v_fmac_f32_e32 v203, v204, v203
	v_div_scale_f32 v204, vcc, 1.0, v157, 1.0
	v_mul_f32_e32 v205, v204, v203
	v_fma_f32 v254, -v151, v205, v204
	v_fmac_f32_e32 v205, v254, v203
	v_fma_f32 v151, -v151, v205, v204
	v_div_fmas_f32 v151, v151, v203, v205
	v_div_fixup_f32 v155, v151, v157, 1.0
	v_mul_f32_e32 v66, v66, v155
	v_mul_f32_e32 v67, v67, v155
	v_mul_f32_e32 v68, v68, v155
	v_mul_f32_e32 v69, v69, v155
	v_pk_fma_f32 v[66:67], v[2:3], v[66:67], v[10:11]
	v_pk_fma_f32 v[68:69], v[4:5], v[68:69], v[12:13]
	global_store_dwordx4 v129, v[66:69], s[6:7]
	s_waitcnt vmcnt(15)
	v_pk_add_f32 v[158:159], v[158:159], 1.0 op_sel_hi:[1,0]
	v_pk_add_f32 v[160:161], v[160:161], 1.0 op_sel_hi:[1,0]
	v_pk_fma_f32 v[158:159], v[158:159], v[66:67], v[220:221]
	v_pk_fma_f32 v[160:161], v[160:161], v[68:69], v[222:223]
	v_cvt_pk_bf16_f32 v158, v158, v159
	v_cvt_pk_bf16_f32 v159, v160, v161
	global_store_dwordx2 v117, v[158:159], s[10:11]
	v_mul_f32_e32 v70, v70, v155
	v_mul_f32_e32 v71, v71, v155
	v_mul_f32_e32 v72, v72, v155
	v_mul_f32_e32 v73, v73, v155
	v_pk_fma_f32 v[70:71], v[6:7], v[70:71], v[14:15]
	v_pk_fma_f32 v[72:73], v[8:9], v[72:73], v[16:17]
	global_store_dwordx4 v129, v[70:73], s[6:7] offset:1024
	s_waitcnt vmcnt(15)
	v_pk_add_f32 v[162:163], v[162:163], 1.0 op_sel_hi:[1,0]
	v_pk_add_f32 v[164:165], v[164:165], 1.0 op_sel_hi:[1,0]
	v_pk_fma_f32 v[162:163], v[162:163], v[70:71], v[224:225]
	v_pk_fma_f32 v[164:165], v[164:165], v[72:73], v[226:227]
	v_cvt_pk_bf16_f32 v162, v162, v163
	v_cvt_pk_bf16_f32 v163, v164, v165
	global_store_dwordx2 v117, v[162:163], s[10:11] offset:512
	v_mul_f32_e32 v74, v74, v155
	v_mul_f32_e32 v75, v75, v155
	v_mul_f32_e32 v76, v76, v155
	v_mul_f32_e32 v77, v77, v155
	v_pk_fma_f32 v[74:75], v[18:19], v[74:75], v[26:27]
	v_pk_fma_f32 v[76:77], v[20:21], v[76:77], v[28:29]
	global_store_dwordx4 v129, v[74:77], s[6:7] offset:2048
	s_waitcnt vmcnt(15)
	v_pk_add_f32 v[166:167], v[166:167], 1.0 op_sel_hi:[1,0]
	v_pk_add_f32 v[168:169], v[168:169], 1.0 op_sel_hi:[1,0]
	v_pk_fma_f32 v[166:167], v[166:167], v[74:75], v[228:229]
	v_pk_fma_f32 v[168:169], v[168:169], v[76:77], v[230:231]
	v_cvt_pk_bf16_f32 v166, v166, v167
	v_cvt_pk_bf16_f32 v167, v168, v169
	global_store_dwordx2 v117, v[166:167], s[10:11] offset:1024
	v_mul_f32_e32 v78, v78, v155
	v_mul_f32_e32 v79, v79, v155
	v_mul_f32_e32 v80, v80, v155
	v_mul_f32_e32 v81, v81, v155
	v_pk_fma_f32 v[78:79], v[22:23], v[78:79], v[30:31]
	v_pk_fma_f32 v[80:81], v[24:25], v[80:81], v[32:33]
	global_store_dwordx4 v129, v[78:81], s[6:7] offset:3072
	s_waitcnt vmcnt(15)
	v_pk_add_f32 v[176:177], v[176:177], 1.0 op_sel_hi:[1,0]
	v_pk_add_f32 v[178:179], v[178:179], 1.0 op_sel_hi:[1,0]
	v_pk_fma_f32 v[176:177], v[176:177], v[78:79], v[232:233]
	v_pk_fma_f32 v[178:179], v[178:179], v[80:81], v[234:235]
	v_cvt_pk_bf16_f32 v176, v176, v177
	v_cvt_pk_bf16_f32 v177, v178, v179
	global_store_dwordx2 v117, v[176:177], s[10:11] offset:1536
	v_mul_f32_e32 v82, v82, v155
	v_mul_f32_e32 v83, v83, v155
	v_mul_f32_e32 v84, v84, v155
	v_mul_f32_e32 v85, v85, v155
	v_pk_fma_f32 v[82:83], v[34:35], v[82:83], v[42:43]
	v_pk_fma_f32 v[84:85], v[36:37], v[84:85], v[44:45]
	global_store_dwordx4 v131, v[82:85], s[6:7]
	s_waitcnt vmcnt(15)
	v_pk_add_f32 v[180:181], v[180:181], 1.0 op_sel_hi:[1,0]
	v_pk_add_f32 v[182:183], v[182:183], 1.0 op_sel_hi:[1,0]
	v_pk_fma_f32 v[180:181], v[180:181], v[82:83], v[236:237]
	v_pk_fma_f32 v[182:183], v[182:183], v[84:85], v[238:239]
	v_cvt_pk_bf16_f32 v180, v180, v181
	v_cvt_pk_bf16_f32 v181, v182, v183
	global_store_dwordx2 v117, v[180:181], s[10:11] offset:2048
	v_mul_f32_e32 v86, v86, v155
	v_mul_f32_e32 v87, v87, v155
	v_mul_f32_e32 v88, v88, v155
	v_mul_f32_e32 v89, v89, v155
	v_pk_fma_f32 v[86:87], v[38:39], v[86:87], v[46:47]
	v_pk_fma_f32 v[88:89], v[40:41], v[88:89], v[48:49]
	global_store_dwordx4 v131, v[86:89], s[6:7] offset:1024
	s_waitcnt vmcnt(15)
	v_pk_add_f32 v[184:185], v[184:185], 1.0 op_sel_hi:[1,0]
	v_pk_add_f32 v[186:187], v[186:187], 1.0 op_sel_hi:[1,0]
	v_pk_fma_f32 v[184:185], v[184:185], v[86:87], v[240:241]
	v_pk_fma_f32 v[186:187], v[186:187], v[88:89], v[242:243]
	v_cvt_pk_bf16_f32 v184, v184, v185
	v_cvt_pk_bf16_f32 v185, v186, v187
	global_store_dwordx2 v117, v[184:185], s[10:11] offset:2560
	v_mul_f32_e32 v90, v90, v155
	v_mul_f32_e32 v91, v91, v155
	v_mul_f32_e32 v92, v92, v155
	v_mul_f32_e32 v93, v93, v155
	v_pk_fma_f32 v[90:91], v[50:51], v[90:91], v[58:59]
	v_pk_fma_f32 v[92:93], v[52:53], v[92:93], v[60:61]
	global_store_dwordx4 v131, v[90:93], s[6:7] offset:2048
	s_waitcnt vmcnt(15)
	v_pk_add_f32 v[212:213], v[212:213], 1.0 op_sel_hi:[1,0]
	v_pk_add_f32 v[214:215], v[214:215], 1.0 op_sel_hi:[1,0]
	v_pk_fma_f32 v[212:213], v[212:213], v[90:91], v[244:245]
	v_pk_fma_f32 v[214:215], v[214:215], v[92:93], v[246:247]
	v_cvt_pk_bf16_f32 v212, v212, v213
	v_cvt_pk_bf16_f32 v213, v214, v215
	global_store_dwordx2 v117, v[212:213], s[10:11] offset:3072
	v_mul_f32_e32 v94, v94, v155
	v_mul_f32_e32 v95, v95, v155
	v_mul_f32_e32 v96, v96, v155
	v_mul_f32_e32 v97, v97, v155
	v_pk_fma_f32 v[94:95], v[54:55], v[94:95], v[62:63]
	v_pk_fma_f32 v[96:97], v[56:57], v[96:97], v[64:65]
	global_store_dwordx4 v131, v[94:97], s[6:7] offset:3072
	s_waitcnt vmcnt(15)
	v_pk_add_f32 v[216:217], v[216:217], 1.0 op_sel_hi:[1,0]
	v_pk_add_f32 v[218:219], v[218:219], 1.0 op_sel_hi:[1,0]
	v_pk_fma_f32 v[216:217], v[216:217], v[94:95], v[248:249]
	v_pk_fma_f32 v[218:219], v[218:219], v[96:97], v[250:251]
	v_cvt_pk_bf16_f32 v216, v216, v217
	v_cvt_pk_bf16_f32 v217, v218, v219
	global_store_dwordx2 v117, v[216:217], s[10:11] offset:3584
.Lp6_r3_done:
	s_waitcnt vmcnt(0)
	s_cmp_lt_i32 s69, 0
	s_cbranch_scc1 .Lp6_done
	s_mov_b32 s0, s69
	s_lshl_b32 s1, s0, 13
	s_add_u32 s6, s40, s1
	s_addc_u32 s7, s41, 0
	s_lshl_b32 s1, s0, 12
	s_add_u32 s10, s44, s1
	s_addc_u32 s11, s45, 0
	s_lshr_b32 s1, s0, 11
	s_lshl_b32 s1, s1, 16
	s_add_u32 s16, s14, s1
	s_addc_u32 s17, s15, 0
	global_load_dwordx4 v[66:69], v129, s[6:7]
	global_load_dwordx4 v[70:73], v129, s[6:7] offset:1024
	global_load_dwordx4 v[74:77], v129, s[6:7] offset:2048
	global_load_dwordx4 v[78:81], v129, s[6:7] offset:3072
	global_load_dwordx4 v[82:85], v131, s[6:7]
	global_load_dwordx4 v[86:89], v131, s[6:7] offset:1024
	global_load_dwordx4 v[90:93], v131, s[6:7] offset:2048
	global_load_dwordx4 v[94:97], v131, s[6:7] offset:3072
	v_lshlrev_b32_e32 v151, 2, v116
	global_load_dwordx4 v[158:161], v151, s[16:17]
	v_lshlrev_b32_e32 v151, 2, v118
	global_load_dwordx4 v[220:223], v151, s[16:17]
	v_lshlrev_b32_e32 v151, 2, v120
	global_load_dwordx4 v[162:165], v151, s[16:17]
	v_lshlrev_b32_e32 v151, 2, v122
	global_load_dwordx4 v[224:227], v151, s[16:17]
	v_lshlrev_b32_e32 v151, 2, v124
	global_load_dwordx4 v[166:169], v151, s[16:17]
	v_lshlrev_b32_e32 v151, 2, v126
	global_load_dwordx4 v[228:231], v151, s[16:17]
	v_lshlrev_b32_e32 v151, 2, v128
	global_load_dwordx4 v[176:179], v151, s[16:17]
	v_lshlrev_b32_e32 v151, 2, v130
	global_load_dwordx4 v[232:235], v151, s[16:17]
	v_lshlrev_b32_e32 v151, 2, v132
	global_load_dwordx4 v[180:183], v151, s[16:17]
	v_lshlrev_b32_e32 v151, 2, v134
	global_load_dwordx4 v[236:239], v151, s[16:17]
	v_lshlrev_b32_e32 v151, 2, v136
	global_load_dwordx4 v[184:187], v151, s[16:17]
	v_lshlrev_b32_e32 v151, 2, v138
	global_load_dwordx4 v[240:243], v151, s[16:17]
	v_lshlrev_b32_e32 v151, 2, v140
	global_load_dwordx4 v[212:215], v151, s[16:17]
	v_lshlrev_b32_e32 v151, 2, v142
	global_load_dwordx4 v[244:247], v151, s[16:17]
	v_lshlrev_b32_e32 v151, 2, v144
	global_load_dwordx4 v[216:219], v151, s[16:17]
	v_lshlrev_b32_e32 v151, 2, v146
	global_load_dwordx4 v[248:251], v151, s[16:17]
	s_waitcnt vmcnt(23)
	v_add_f32_e32 v151, v66, v67
	v_add_f32_e32 v155, v68, v69
	v_add_f32_e32 v151, v151, v155
	v_add_f32_e32 v153, 0, v151
	s_waitcnt vmcnt(22)
	v_add_f32_e32 v151, v70, v71
	v_add_f32_e32 v155, v72, v73
	v_add_f32_e32 v151, v151, v155
	v_add_f32_e32 v153, v153, v151
	s_waitcnt vmcnt(21)
	v_add_f32_e32 v151, v74, v75
	v_add_f32_e32 v155, v76, v77
	v_add_f32_e32 v151, v151, v155
	v_add_f32_e32 v153, v153, v151
	s_waitcnt vmcnt(20)
	v_add_f32_e32 v151, v78, v79
	v_add_f32_e32 v155, v80, v81
	v_add_f32_e32 v151, v151, v155
	v_add_f32_e32 v153, v153, v151
	s_waitcnt vmcnt(19)
	v_add_f32_e32 v151, v82, v83
	v_add_f32_e32 v155, v84, v85
	v_add_f32_e32 v151, v151, v155
	v_add_f32_e32 v153, v153, v151
	s_waitcnt vmcnt(18)
	v_add_f32_e32 v151, v86, v87
	v_add_f32_e32 v155, v88, v89
	v_add_f32_e32 v151, v151, v155
	v_add_f32_e32 v153, v153, v151
	s_waitcnt vmcnt(17)
	v_add_f32_e32 v151, v90, v91
	v_add_f32_e32 v155, v92, v93
	v_add_f32_e32 v151, v151, v155
	v_add_f32_e32 v153, v153, v151
	s_waitcnt vmcnt(16)
	v_add_f32_e32 v151, v94, v95
	v_add_f32_e32 v155, v96, v97
	v_add_f32_e32 v151, v151, v155
	v_add_f32_e32 v153, v153, v151
	ds_bpermute_b32 v151, v99, v153
	s_waitcnt lgkmcnt(0)
	v_add_f32_e32 v153, v153, v151
	ds_bpermute_b32 v151, v101, v153
	s_waitcnt lgkmcnt(0)
	v_add_f32_e32 v153, v153, v151
	ds_bpermute_b32 v151, v103, v153
	s_waitcnt lgkmcnt(0)
	v_add_f32_e32 v153, v153, v151
	ds_bpermute_b32 v151, v105, v153
	s_waitcnt lgkmcnt(0)
	v_add_f32_e32 v153, v153, v151
	ds_bpermute_b32 v151, v107, v153
	s_waitcnt lgkmcnt(0)
	v_add_f32_e32 v153, v153, v151
	ds_bpermute_b32 v151, v119, v153
	s_waitcnt lgkmcnt(0)
	v_add_f32_e32 v153, v153, v151
	v_fmac_f32_e32 v66, 0xba000000, v153
	v_fmac_f32_e32 v67, 0xba000000, v153
	v_fmac_f32_e32 v68, 0xba000000, v153
	v_fmac_f32_e32 v69, 0xba000000, v153
	v_fmac_f32_e32 v70, 0xba000000, v153
	v_fmac_f32_e32 v71, 0xba000000, v153
	v_fmac_f32_e32 v72, 0xba000000, v153
	v_fmac_f32_e32 v73, 0xba000000, v153
	v_fmac_f32_e32 v74, 0xba000000, v153
	v_fmac_f32_e32 v75, 0xba000000, v153
	v_fmac_f32_e32 v76, 0xba000000, v153
	v_fmac_f32_e32 v77, 0xba000000, v153
	v_fmac_f32_e32 v78, 0xba000000, v153
	v_fmac_f32_e32 v79, 0xba000000, v153
	v_fmac_f32_e32 v80, 0xba000000, v153
	v_fmac_f32_e32 v81, 0xba000000, v153
	v_fmac_f32_e32 v82, 0xba000000, v153
	v_fmac_f32_e32 v83, 0xba000000, v153
	v_fmac_f32_e32 v84, 0xba000000, v153
	v_fmac_f32_e32 v85, 0xba000000, v153
	v_fmac_f32_e32 v86, 0xba000000, v153
	v_fmac_f32_e32 v87, 0xba000000, v153
	v_fmac_f32_e32 v88, 0xba000000, v153
	v_fmac_f32_e32 v89, 0xba000000, v153
	v_fmac_f32_e32 v90, 0xba000000, v153
	v_fmac_f32_e32 v91, 0xba000000, v153
	v_fmac_f32_e32 v92, 0xba000000, v153
	v_fmac_f32_e32 v93, 0xba000000, v153
	v_fmac_f32_e32 v94, 0xba000000, v153
	v_fmac_f32_e32 v95, 0xba000000, v153
	v_fmac_f32_e32 v96, 0xba000000, v153
	v_fmac_f32_e32 v97, 0xba000000, v153
	v_mul_f32_e32 v151, v67, v67
	v_fma_f32 v151, v66, v66, v151
	v_mul_f32_e32 v155, v69, v69
	v_fma_f32 v155, v68, v68, v155
	v_add_f32_e32 v151, v151, v155
	v_add_f32_e32 v157, 0, v151
	v_mul_f32_e32 v151, v71, v71
	v_fma_f32 v151, v70, v70, v151
	v_mul_f32_e32 v155, v73, v73
	v_fma_f32 v155, v72, v72, v155
	v_add_f32_e32 v151, v151, v155
	v_add_f32_e32 v157, v157, v151
	v_mul_f32_e32 v151, v75, v75
	v_fma_f32 v151, v74, v74, v151
	v_mul_f32_e32 v155, v77, v77
	v_fma_f32 v155, v76, v76, v155
	v_add_f32_e32 v151, v151, v155
	v_add_f32_e32 v157, v157, v151
	v_mul_f32_e32 v151, v79, v79
	v_fma_f32 v151, v78, v78, v151
	v_mul_f32_e32 v155, v81, v81
	v_fma_f32 v155, v80, v80, v155
	v_add_f32_e32 v151, v151, v155
	v_add_f32_e32 v157, v157, v151
	v_mul_f32_e32 v151, v83, v83
	v_fma_f32 v151, v82, v82, v151
	v_mul_f32_e32 v155, v85, v85
	v_fma_f32 v155, v84, v84, v155
	v_add_f32_e32 v151, v151, v155
	v_add_f32_e32 v157, v157, v151
	v_mul_f32_e32 v151, v87, v87
	v_fma_f32 v151, v86, v86, v151
	v_mul_f32_e32 v155, v89, v89
	v_fma_f32 v155, v88, v88, v155
	v_add_f32_e32 v151, v151, v155
	v_add_f32_e32 v157, v157, v151
	v_mul_f32_e32 v151, v91, v91
	v_fma_f32 v151, v90, v90, v151
	v_mul_f32_e32 v155, v93, v93
	v_fma_f32 v155, v92, v92, v155
	v_add_f32_e32 v151, v151, v155
	v_add_f32_e32 v157, v157, v151
	v_mul_f32_e32 v151, v95, v95
	v_fma_f32 v151, v94, v94, v151
	v_mul_f32_e32 v155, v97, v97
	v_fma_f32 v155, v96, v96, v155
	v_add_f32_e32 v151, v151, v155
	v_add_f32_e32 v157, v157, v151
	ds_bpermute_b32 v151, v99, v157
	s_waitcnt lgkmcnt(0)
	v_add_f32_e32 v157, v157, v151
	ds_bpermute_b32 v151, v101, v157
	s_waitcnt lgkmcnt(0)
	v_add_f32_e32 v157, v157, v151
	ds_bpermute_b32 v151, v103, v157
	s_waitcnt lgkmcnt(0)
	v_add_f32_e32 v157, v157, v151
	ds_bpermute_b32 v151, v105, v157
	s_waitcnt lgkmcnt(0)
	v_add_f32_e32 v157, v157, v151
	ds_bpermute_b32 v151, v107, v157
	s_waitcnt lgkmcnt(0)
	v_add_f32_e32 v157, v157, v151
	ds_bpermute_b32 v151, v119, v157
	s_waitcnt lgkmcnt(0)
	v_add_f32_e32 v157, v157, v151
	v_mov_b32_e32 v254, 0x3727c5ac
	v_fmamk_f32 v157, v157, 0x3a000000, v254
	v_mul_f32_e32 v151, 0x4f800000, v157
	s_mov_b32 s9, 0xf800000
	v_cmp_gt_f32_e32 vcc, s9, v157
	s_nop 1
	v_cndmask_b32_e32 v157, v157, v151, vcc
	v_sqrt_f32_e32 v151, v157
	s_nop 0
	v_add_u32_e32 v203, -1, v151
	v_fma_f32 v204, -v203, v151, v157
	v_cmp_ge_f32_e64 s[88:89], 0, v204
	v_add_u32_e32 v204, 1, v151
	s_nop 0
	v_cndmask_b32_e64 v203, v151, v203, s[88:89]
	v_fma_f32 v151, -v204, v151, v157
	v_cmp_lt_f32_e64 s[88:89], 0, v151
	s_nop 1
	v_cndmask_b32_e64 v151, v203, v204, s[88:89]
	v_mul_f32_e32 v203, 0x37800000, v151
	v_cndmask_b32_e32 v151, v151, v203, vcc
	v_mov_b32_e32 v203, 0x260
	v_cmp_class_f32_e32 vcc, v157, v203
	s_nop 1
	v_cndmask_b32_e32 v157, v151, v157, vcc
	v_div_scale_f32 v151, s[88:89], v157, v157, 1.0
	v_rcp_f32_e32 v203, v151
	s_nop 0
	v_fma_f32 v204, -v151, v203, 1.0
	v_fmac_f32_e32 v203, v204, v203
	v_div_scale_f32 v204, vcc, 1.0, v157, 1.0
	v_mul_f32_e32 v205, v204, v203
	v_fma_f32 v254, -v151, v205, v204
	v_fmac_f32_e32 v205, v254, v203
	v_fma_f32 v151, -v151, v205, v204
	v_div_fmas_f32 v151, v151, v203, v205
	v_div_fixup_f32 v155, v151, v157, 1.0
	v_mul_f32_e32 v66, v66, v155
	v_mul_f32_e32 v67, v67, v155
	v_mul_f32_e32 v68, v68, v155
	v_mul_f32_e32 v69, v69, v155
	v_pk_fma_f32 v[66:67], v[2:3], v[66:67], v[10:11]
	v_pk_fma_f32 v[68:69], v[4:5], v[68:69], v[12:13]
	global_store_dwordx4 v129, v[66:69], s[6:7]
	s_waitcnt vmcnt(15)
	v_pk_add_f32 v[158:159], v[158:159], 1.0 op_sel_hi:[1,0]
	v_pk_add_f32 v[160:161], v[160:161], 1.0 op_sel_hi:[1,0]
	v_pk_fma_f32 v[158:159], v[158:159], v[66:67], v[220:221]
	v_pk_fma_f32 v[160:161], v[160:161], v[68:69], v[222:223]
	v_cvt_pk_bf16_f32 v158, v158, v159
	v_cvt_pk_bf16_f32 v159, v160, v161
	global_store_dwordx2 v117, v[158:159], s[10:11]
	v_mul_f32_e32 v70, v70, v155
	v_mul_f32_e32 v71, v71, v155
	v_mul_f32_e32 v72, v72, v155
	v_mul_f32_e32 v73, v73, v155
	v_pk_fma_f32 v[70:71], v[6:7], v[70:71], v[14:15]
	v_pk_fma_f32 v[72:73], v[8:9], v[72:73], v[16:17]
	global_store_dwordx4 v129, v[70:73], s[6:7] offset:1024
	s_waitcnt vmcnt(15)
	v_pk_add_f32 v[162:163], v[162:163], 1.0 op_sel_hi:[1,0]
	v_pk_add_f32 v[164:165], v[164:165], 1.0 op_sel_hi:[1,0]
	v_pk_fma_f32 v[162:163], v[162:163], v[70:71], v[224:225]
	v_pk_fma_f32 v[164:165], v[164:165], v[72:73], v[226:227]
	v_cvt_pk_bf16_f32 v162, v162, v163
	v_cvt_pk_bf16_f32 v163, v164, v165
	global_store_dwordx2 v117, v[162:163], s[10:11] offset:512
	v_mul_f32_e32 v74, v74, v155
	v_mul_f32_e32 v75, v75, v155
	v_mul_f32_e32 v76, v76, v155
	v_mul_f32_e32 v77, v77, v155
	v_pk_fma_f32 v[74:75], v[18:19], v[74:75], v[26:27]
	v_pk_fma_f32 v[76:77], v[20:21], v[76:77], v[28:29]
	global_store_dwordx4 v129, v[74:77], s[6:7] offset:2048
	s_waitcnt vmcnt(15)
	v_pk_add_f32 v[166:167], v[166:167], 1.0 op_sel_hi:[1,0]
	v_pk_add_f32 v[168:169], v[168:169], 1.0 op_sel_hi:[1,0]
	v_pk_fma_f32 v[166:167], v[166:167], v[74:75], v[228:229]
	v_pk_fma_f32 v[168:169], v[168:169], v[76:77], v[230:231]
	v_cvt_pk_bf16_f32 v166, v166, v167
	v_cvt_pk_bf16_f32 v167, v168, v169
	global_store_dwordx2 v117, v[166:167], s[10:11] offset:1024
	v_mul_f32_e32 v78, v78, v155
	v_mul_f32_e32 v79, v79, v155
	v_mul_f32_e32 v80, v80, v155
	v_mul_f32_e32 v81, v81, v155
	v_pk_fma_f32 v[78:79], v[22:23], v[78:79], v[30:31]
	v_pk_fma_f32 v[80:81], v[24:25], v[80:81], v[32:33]
	global_store_dwordx4 v129, v[78:81], s[6:7] offset:3072
	s_waitcnt vmcnt(15)
	v_pk_add_f32 v[176:177], v[176:177], 1.0 op_sel_hi:[1,0]
	v_pk_add_f32 v[178:179], v[178:179], 1.0 op_sel_hi:[1,0]
	v_pk_fma_f32 v[176:177], v[176:177], v[78:79], v[232:233]
	v_pk_fma_f32 v[178:179], v[178:179], v[80:81], v[234:235]
	v_cvt_pk_bf16_f32 v176, v176, v177
	v_cvt_pk_bf16_f32 v177, v178, v179
	global_store_dwordx2 v117, v[176:177], s[10:11] offset:1536
	v_mul_f32_e32 v82, v82, v155
	v_mul_f32_e32 v83, v83, v155
	v_mul_f32_e32 v84, v84, v155
	v_mul_f32_e32 v85, v85, v155
	v_pk_fma_f32 v[82:83], v[34:35], v[82:83], v[42:43]
	v_pk_fma_f32 v[84:85], v[36:37], v[84:85], v[44:45]
	global_store_dwordx4 v131, v[82:85], s[6:7]
	s_waitcnt vmcnt(15)
	v_pk_add_f32 v[180:181], v[180:181], 1.0 op_sel_hi:[1,0]
	v_pk_add_f32 v[182:183], v[182:183], 1.0 op_sel_hi:[1,0]
	v_pk_fma_f32 v[180:181], v[180:181], v[82:83], v[236:237]
	v_pk_fma_f32 v[182:183], v[182:183], v[84:85], v[238:239]
	v_cvt_pk_bf16_f32 v180, v180, v181
	v_cvt_pk_bf16_f32 v181, v182, v183
	global_store_dwordx2 v117, v[180:181], s[10:11] offset:2048
	v_mul_f32_e32 v86, v86, v155
	v_mul_f32_e32 v87, v87, v155
	v_mul_f32_e32 v88, v88, v155
	v_mul_f32_e32 v89, v89, v155
	v_pk_fma_f32 v[86:87], v[38:39], v[86:87], v[46:47]
	v_pk_fma_f32 v[88:89], v[40:41], v[88:89], v[48:49]
	global_store_dwordx4 v131, v[86:89], s[6:7] offset:1024
	s_waitcnt vmcnt(15)
	v_pk_add_f32 v[184:185], v[184:185], 1.0 op_sel_hi:[1,0]
	v_pk_add_f32 v[186:187], v[186:187], 1.0 op_sel_hi:[1,0]
	v_pk_fma_f32 v[184:185], v[184:185], v[86:87], v[240:241]
	v_pk_fma_f32 v[186:187], v[186:187], v[88:89], v[242:243]
	v_cvt_pk_bf16_f32 v184, v184, v185
	v_cvt_pk_bf16_f32 v185, v186, v187
	global_store_dwordx2 v117, v[184:185], s[10:11] offset:2560
	v_mul_f32_e32 v90, v90, v155
	v_mul_f32_e32 v91, v91, v155
	v_mul_f32_e32 v92, v92, v155
	v_mul_f32_e32 v93, v93, v155
	v_pk_fma_f32 v[90:91], v[50:51], v[90:91], v[58:59]
	v_pk_fma_f32 v[92:93], v[52:53], v[92:93], v[60:61]
	global_store_dwordx4 v131, v[90:93], s[6:7] offset:2048
	s_waitcnt vmcnt(15)
	v_pk_add_f32 v[212:213], v[212:213], 1.0 op_sel_hi:[1,0]
	v_pk_add_f32 v[214:215], v[214:215], 1.0 op_sel_hi:[1,0]
	v_pk_fma_f32 v[212:213], v[212:213], v[90:91], v[244:245]
	v_pk_fma_f32 v[214:215], v[214:215], v[92:93], v[246:247]
	v_cvt_pk_bf16_f32 v212, v212, v213
	v_cvt_pk_bf16_f32 v213, v214, v215
	global_store_dwordx2 v117, v[212:213], s[10:11] offset:3072
	v_mul_f32_e32 v94, v94, v155
	v_mul_f32_e32 v95, v95, v155
	v_mul_f32_e32 v96, v96, v155
	v_mul_f32_e32 v97, v97, v155
	v_pk_fma_f32 v[94:95], v[54:55], v[94:95], v[62:63]
	v_pk_fma_f32 v[96:97], v[56:57], v[96:97], v[64:65]
	global_store_dwordx4 v131, v[94:97], s[6:7] offset:3072
	s_waitcnt vmcnt(15)
	v_pk_add_f32 v[216:217], v[216:217], 1.0 op_sel_hi:[1,0]
	v_pk_add_f32 v[218:219], v[218:219], 1.0 op_sel_hi:[1,0]
	v_pk_fma_f32 v[216:217], v[216:217], v[94:95], v[248:249]
	v_pk_fma_f32 v[218:219], v[218:219], v[96:97], v[250:251]
	v_cvt_pk_bf16_f32 v216, v216, v217
	v_cvt_pk_bf16_f32 v217, v218, v219
	global_store_dwordx2 v117, v[216:217], s[10:11] offset:3584
.Lp6_done:
.LBB0_755:
	s_waitcnt vmcnt(0)
	s_barrier
	s_mov_b64 s[6:7], exec
	v_readlane_b32 s0, v255, 3
	v_readlane_b32 s1, v255, 4
	s_and_b64 s[0:1], s[6:7], s[0:1]
	s_mov_b64 exec, s[0:1]
	s_cbranch_execz .LBB0_807
	s_add_i32 s0, 0, 0x20000
	s_waitcnt vmcnt(15)
	v_mov_b32_e32 v2, s0
	s_waitcnt vmcnt(0) expcnt(0) lgkmcnt(0)
	ds_read_b32 v4, v2
	s_add_i32 s0, 0, 0x20004
	v_mov_b32_e32 v2, s0
	ds_read_b32 v2, v2
	s_waitcnt lgkmcnt(1)
	v_cmp_ne_u32_e32 vcc, 0, v4
	s_cbranch_vccnz .LBB0_771
	v_readlane_b32 s8, v255, 0
	v_readlane_b32 s9, v255, 1
	s_load_dwordx2 s[0:1], s[8:9], 0x4
	s_add_u32 s8, s70, 0x1000
	s_addc_u32 s9, s71, 0
	s_add_u32 s16, s70, 0x1100
	s_addc_u32 s17, s71, 0
	s_add_u32 s50, s70, 0x1200
	s_addc_u32 s51, s71, 0
	s_waitcnt lgkmcnt(0)
	s_mul_i32 s0, s0, s96
	s_add_u32 s54, s70, 0x1300
	s_mul_i32 s0, s0, s1
	s_addc_u32 s55, s71, 0
	s_mov_b32 s1, 1
	v_mov_b32_e32 v18, 0
	s_branch .LBB0_759
